# scan deserialize + fox L2 prefetch dummies (no fast path)
# speedup vs baseline: 1.0269x; 1.0051x over previous
; DI void fox_unit(const Params& p, int hf, int bl, int fh, int qb, unsigned char* shm, int tid, bool dry = false) {
;     ...
;     if (kt + 1 < nkt) {
;       const size_t r = (size_t)((kt + 1) * 64 + skey) * NP;
;       kreg = *(const uint4*)(projb + r + C_FK + fh * 64 + sdg * 8); vreg = *(const uint4*)(projb + r + C_FV + fh * 64 + sdg * 8);
;       if (tid < 64) freg = (Fref - F[(kt + 1) * 64 + tid]) * LOG2E;
;     }
.LBB0_486:
	v_add_u32_e32 v18, s18, v217
	v_mov_b64_e32 v[16:17], s[6:7]
	v_mad_i64_i32 v[16:17], s[4:5], v18, s65, v[16:17]
	v_lshl_add_u64 v[16:17], v[16:17], 0, s[2:3]
	v_lshl_add_u64 v[16:17], v[16:17], 0, v[160:161]
	v_add_co_u32_e32 v18, vcc, 0x1000, v16
	s_nop 1
	v_addc_co_u32_e32 v19, vcc, 0, v17, vcc
	v_add_co_u32_e32 v20, vcc, 0x2000, v16
	s_nop 1
	v_addc_co_u32_e32 v21, vcc, 0, v17, vcc
	s_mov_b32 s100, 0x270000
	s_mov_b32 s101, 0
	v_lshl_add_u64 v[100:101], v[18:19], 0, s[100:101]
	v_lshl_add_u64 v[102:103], v[20:21], 0, s[100:101]
	global_load_dwordx4 v[16:19], v[18:19], off offset:3072
	s_nop 0
	global_load_dwordx4 v[20:23], v[20:21], off
	s_and_saveexec_b64 s[4:5], s[0:1]
	s_cbranch_execz .LBB0_488
	v_add_u32_e32 v24, s18, v216
	v_ashrrev_i32_e32 v25, 31, v24
	v_lshl_add_u64 v[24:25], v[24:25], 2, s[8:9]
	global_load_dword v208, v[24:25], off
.LBB0_488:
	s_or_b64 exec, exec, s[4:5]
	global_load_dword v198, v[100:101], off offset:3072
	global_load_dword v199, v[102:103], off
	s_and_b32 s21, s22, 1
	v_cmp_le_i32_e32 vcc, s18, v212
	s_and_saveexec_b64 s[14:15], vcc
	s_cbranch_execz .LBB0_485

; DI void fox_unit(const Params& p, int hf, int bl, int fh, int qb, unsigned char* shm, int tid, bool dry = false) {
;     ...
;     if (kt + 1 < nkt) {
;       bf16_t* nK = (bf16_t*)(shm + (st ^ 1) * STG); bf16_t* nV = nK + 64 * 72; float* nF = (float*)(nV + 64 * 72);
;       *(uint4*)((unsigned char*)nK + kst) = kreg; *(uint4*)(nV + skey * 72 + sdg * 8) = vreg;
;       if (tid < 64) nF[tid] = freg;
;     }
.LBB0_494:
	s_xor_b32 s4, s21, 1
	s_mulk_i32 s4, 0x4900
	s_add_i32 s12, s4, 32
	s_waitcnt lgkmcnt(0)
	v_add_u32_e32 v24, s12, v210
	s_waitcnt vmcnt(3)
	ds_write_b128 v24, v[16:19]
	v_add3_u32 v24, s12, v211, v160
	s_waitcnt vmcnt(2)
	ds_write_b128 v24, v[20:23] offset:9216
	s_and_saveexec_b64 s[4:5], s[0:1]
	v_sub_f32_e32 v208, v192, v208
	v_lshl_add_u32 v24, v205, 2, s12
	v_mul_f32_e32 v208, 0x3fb8aa3b, v208
	ds_write_b32 v24, v208 offset:18432
	s_or_b64 exec, exec, s[4:5]

; DI unsigned pk2(float lo, float hi) { unsigned r; asm volatile("v_cvt_pk_bf16_f32 %0, %1, %2" : "=v"(r) : "v"(lo), "v"(hi)); return r; }
; DI void scan_unit(const Params& p, int hf, int su, int tid) {
;     ...
;     } else {
;       const int k = i - n_r, bl = k / 32768, h = (k / 2048) & 15, e = (k & 2047) * 4;
;       float S0 = 0.f, S1 = 0.f, S2 = 0.f, S3 = 0.f;
;       const float* ptr = sst + (size_t)(bl * 64 * 16 + h) * 8192 + e;
;       bf16_t* pp = (bf16_t*)(wsb + WS_SSTP + (size_t)hf * HROWS * DM * 2) + (size_t)(bl * 64 * 16 + h) * 8192 + e;
; #pragma unroll 8
;       for (int c = 0; c < 64; ++c) {
;         const float4 lo = *(const float4*)(ptr + (size_t)c * 16 * 8192);
;         uint2 w; w.x = pk2(S0, S1); w.y = pk2(S2, S3); *(uint2*)(pp + (size_t)c * 16 * 8192) = w;
;         const float dc = __expf(asum[(bl * 64 + c) * 16 + h]);
;         S0 = S0 * dc + lo.x; S1 = S1 * dc + lo.y; S2 = S2 * dc + lo.z; S3 = S3 * dc + lo.w;
;       }
;     }
.LBB0_579:
	s_add_u32 s8, s38, 0x17600000
	s_addc_u32 s9, s39, 0
	s_mov_b64 s[10:11], s[38:39]
	s_add_u32 s98, s38, 0xd000000
	s_addc_u32 s99, s39, 0
	global_load_dwordx4 v[48:51], v8, s[8:9]
	s_add_u32 s8, s8, 0x80000
	s_addc_u32 s9, s9, 0
	global_load_dwordx4 v[52:55], v8, s[8:9]
	s_add_u32 s8, s8, 0x80000
	s_addc_u32 s9, s9, 0
	global_load_dwordx4 v[56:59], v8, s[8:9]
	s_add_u32 s8, s8, 0x80000
	s_addc_u32 s9, s9, 0
	global_load_dwordx4 v[60:63], v8, s[8:9]
	s_add_u32 s8, s8, 0x80000
	s_addc_u32 s9, s9, 0
	global_load_dwordx4 v[64:67], v8, s[8:9]
	s_add_u32 s8, s8, 0x80000
	s_addc_u32 s9, s9, 0
	global_load_dwordx4 v[68:71], v8, s[8:9]
	s_add_u32 s8, s8, 0x80000
	s_addc_u32 s9, s9, 0
	global_load_dwordx4 v[72:75], v8, s[8:9]
	s_add_u32 s8, s8, 0x80000
	s_addc_u32 s9, s9, 0
	global_load_dwordx4 v[76:79], v8, s[8:9]
	s_add_u32 s8, s8, 0x80000
	s_addc_u32 s9, s9, 0
	global_load_dwordx4 v[80:83], v8, s[8:9]
	s_add_u32 s8, s8, 0x80000
	s_addc_u32 s9, s9, 0
	global_load_dwordx4 v[84:87], v8, s[8:9]
	s_add_u32 s8, s8, 0x80000
	s_addc_u32 s9, s9, 0
	global_load_dwordx4 v[88:91], v8, s[8:9]
	s_add_u32 s8, s8, 0x80000
	s_addc_u32 s9, s9, 0
	global_load_dwordx4 v[92:95], v8, s[8:9]
	s_add_u32 s8, s8, 0x80000
	s_addc_u32 s9, s9, 0
	global_load_dwordx4 v[96:99], v8, s[8:9]
	s_add_u32 s8, s8, 0x80000
	s_addc_u32 s9, s9, 0
	global_load_dwordx4 v[100:103], v8, s[8:9]
	s_add_u32 s8, s8, 0x80000
	s_addc_u32 s9, s9, 0
	global_load_dwordx4 v[104:107], v8, s[8:9]
	s_add_u32 s8, s8, 0x80000
	s_addc_u32 s9, s9, 0
	global_load_dwordx4 v[108:111], v8, s[8:9]
	s_add_u32 s8, s8, 0x80000
	s_addc_u32 s9, s9, 0
	global_load_dwordx4 v[112:115], v8, s[8:9]
	s_add_u32 s8, s8, 0x80000
	s_addc_u32 s9, s9, 0
	global_load_dwordx4 v[116:119], v8, s[8:9]
	s_add_u32 s8, s8, 0x80000
	s_addc_u32 s9, s9, 0
	global_load_dwordx4 v[120:123], v8, s[8:9]
	s_add_u32 s8, s8, 0x80000
	s_addc_u32 s9, s9, 0
	global_load_dwordx4 v[124:127], v8, s[8:9]
	s_add_u32 s8, s8, 0x80000
	s_addc_u32 s9, s9, 0
	global_load_dwordx4 v[128:131], v8, s[8:9]
	s_add_u32 s8, s8, 0x80000
	s_addc_u32 s9, s9, 0
	global_load_dwordx4 v[132:135], v8, s[8:9]
	s_add_u32 s8, s8, 0x80000
	s_addc_u32 s9, s9, 0
	global_load_dwordx4 v[136:139], v8, s[8:9]
	s_add_u32 s8, s8, 0x80000
	s_addc_u32 s9, s9, 0
	global_load_dwordx4 v[140:143], v8, s[8:9]
	s_add_u32 s8, s8, 0x80000
	s_addc_u32 s9, s9, 0
	global_load_dwordx4 v[144:147], v8, s[8:9]
	s_add_u32 s8, s8, 0x80000
	s_addc_u32 s9, s9, 0
	global_load_dwordx4 v[148:151], v8, s[8:9]
	s_add_u32 s8, s8, 0x80000
	s_addc_u32 s9, s9, 0
	global_load_dwordx4 v[152:155], v8, s[8:9]
	s_add_u32 s8, s8, 0x80000
	s_addc_u32 s9, s9, 0
	global_load_dwordx4 v[156:159], v8, s[8:9]
	s_add_u32 s8, s8, 0x80000
	s_addc_u32 s9, s9, 0
	global_load_dwordx4 v[204:207], v8, s[8:9]
	s_add_u32 s8, s8, 0x80000
	s_addc_u32 s9, s9, 0
	global_load_dwordx4 v[208:211], v8, s[8:9]
	s_add_u32 s8, s8, 0x80000
	s_addc_u32 s9, s9, 0
	global_load_dwordx4 v[212:215], v8, s[8:9]
	s_add_u32 s8, s8, 0x80000
	s_addc_u32 s9, s9, 0
	global_load_dwordx4 v[216:219], v8, s[8:9]
	s_add_u32 s8, s8, 0x80000
	s_addc_u32 s9, s9, 0
	global_load_dword v220, v24, s[10:11]
	global_load_dword v221, v24, s[10:11] offset:64
	global_load_dword v222, v24, s[10:11] offset:128
	global_load_dword v223, v24, s[10:11] offset:192
	global_load_dword v224, v24, s[10:11] offset:256
	global_load_dword v225, v24, s[10:11] offset:320
	global_load_dword v226, v24, s[10:11] offset:384
	global_load_dword v227, v24, s[10:11] offset:448
	global_load_dword v228, v24, s[10:11] offset:512
	global_load_dword v229, v24, s[10:11] offset:576
	global_load_dword v230, v24, s[10:11] offset:640
	global_load_dword v231, v24, s[10:11] offset:704
	global_load_dword v232, v24, s[10:11] offset:768
	global_load_dword v233, v24, s[10:11] offset:832
	global_load_dword v234, v24, s[10:11] offset:896
	global_load_dword v235, v24, s[10:11] offset:960
	global_load_dword v236, v24, s[10:11] offset:1024
	global_load_dword v237, v24, s[10:11] offset:1088
	global_load_dword v238, v24, s[10:11] offset:1152
	global_load_dword v239, v24, s[10:11] offset:1216
	global_load_dword v240, v24, s[10:11] offset:1280
	global_load_dword v241, v24, s[10:11] offset:1344
	global_load_dword v242, v24, s[10:11] offset:1408
	global_load_dword v243, v24, s[10:11] offset:1472
	global_load_dword v244, v24, s[10:11] offset:1536
	global_load_dword v245, v24, s[10:11] offset:1600
	global_load_dword v246, v24, s[10:11] offset:1664
	global_load_dword v247, v24, s[10:11] offset:1728
	global_load_dword v248, v24, s[10:11] offset:1792
	global_load_dword v249, v24, s[10:11] offset:1856
	global_load_dword v250, v24, s[10:11] offset:1920
	global_load_dword v251, v24, s[10:11] offset:1984
	s_add_u32 s10, s10, 0x800
	s_addc_u32 s11, s11, 0
	s_waitcnt vmcnt(31)
	v_mul_f32_e32 v220, 0x3fb8aa3b, v220
	v_exp_f32_e32 v220, v220
	v_cvt_pk_bf16_f32 v42, v30, v31
	v_cvt_pk_bf16_f32 v43, v32, v33
	global_store_dwordx2 v6, v[42:43], s[98:99]
	s_add_u32 s98, s98, 0x40000
	s_addc_u32 s99, s99, 0
	v_fma_f32 v30, v30, v220, v48
	v_fma_f32 v31, v31, v220, v49
	v_fma_f32 v32, v32, v220, v50
	v_fma_f32 v33, v33, v220, v51
	s_waitcnt vmcnt(31)
	v_mul_f32_e32 v221, 0x3fb8aa3b, v221
	v_exp_f32_e32 v221, v221
	v_cvt_pk_bf16_f32 v42, v30, v31
	v_cvt_pk_bf16_f32 v43, v32, v33
	global_store_dwordx2 v6, v[42:43], s[98:99]
	s_add_u32 s98, s98, 0x40000
	s_addc_u32 s99, s99, 0
	v_fma_f32 v30, v30, v221, v52
	v_fma_f32 v31, v31, v221, v53
	v_fma_f32 v32, v32, v221, v54
	v_fma_f32 v33, v33, v221, v55
	s_waitcnt vmcnt(31)
; DI unsigned pk2(float lo, float hi) { unsigned r; asm volatile("v_cvt_pk_bf16_f32 %0, %1, %2" : "=v"(r) : "v"(lo), "v"(hi)); return r; }
; DI void scan_unit(const Params& p, int hf, int su, int tid) {
;     ...
; #pragma unroll 8
;       for (int c = 0; c < 64; ++c) {
;         const float4 lo = *(const float4*)(ptr + (size_t)c * 16 * 8192);
;         uint2 w; w.x = pk2(S0, S1); w.y = pk2(S2, S3); *(uint2*)(pp + (size_t)c * 16 * 8192) = w;
;         const float dc = __expf(asum[(bl * 64 + c) * 16 + h]);
;         S0 = S0 * dc + lo.x; S1 = S1 * dc + lo.y; S2 = S2 * dc + lo.z; S3 = S3 * dc + lo.w;
;       }
	v_mul_f32_e32 v222, 0x3fb8aa3b, v222
	v_exp_f32_e32 v222, v222
	v_cvt_pk_bf16_f32 v42, v30, v31
	v_cvt_pk_bf16_f32 v43, v32, v33
	global_store_dwordx2 v6, v[42:43], s[98:99]
	s_add_u32 s98, s98, 0x40000
	s_addc_u32 s99, s99, 0
	v_fma_f32 v30, v30, v222, v56
	v_fma_f32 v31, v31, v222, v57
	v_fma_f32 v32, v32, v222, v58
	v_fma_f32 v33, v33, v222, v59
	s_waitcnt vmcnt(31)
	v_mul_f32_e32 v223, 0x3fb8aa3b, v223
	v_exp_f32_e32 v223, v223
	v_cvt_pk_bf16_f32 v42, v30, v31
	v_cvt_pk_bf16_f32 v43, v32, v33
	global_store_dwordx2 v6, v[42:43], s[98:99]
	s_add_u32 s98, s98, 0x40000
	s_addc_u32 s99, s99, 0
	v_fma_f32 v30, v30, v223, v60
	v_fma_f32 v31, v31, v223, v61
	v_fma_f32 v32, v32, v223, v62
	v_fma_f32 v33, v33, v223, v63
	s_waitcnt vmcnt(31)
	v_mul_f32_e32 v224, 0x3fb8aa3b, v224
	v_exp_f32_e32 v224, v224
	v_cvt_pk_bf16_f32 v42, v30, v31
	v_cvt_pk_bf16_f32 v43, v32, v33
	global_store_dwordx2 v6, v[42:43], s[98:99]
	s_add_u32 s98, s98, 0x40000
	s_addc_u32 s99, s99, 0
	v_fma_f32 v30, v30, v224, v64
	v_fma_f32 v31, v31, v224, v65
	v_fma_f32 v32, v32, v224, v66
	v_fma_f32 v33, v33, v224, v67
	s_waitcnt vmcnt(31)
	v_mul_f32_e32 v225, 0x3fb8aa3b, v225
	v_exp_f32_e32 v225, v225
	v_cvt_pk_bf16_f32 v42, v30, v31
	v_cvt_pk_bf16_f32 v43, v32, v33
	global_store_dwordx2 v6, v[42:43], s[98:99]
	s_add_u32 s98, s98, 0x40000
	s_addc_u32 s99, s99, 0
	v_fma_f32 v30, v30, v225, v68
	v_fma_f32 v31, v31, v225, v69
	v_fma_f32 v32, v32, v225, v70
	v_fma_f32 v33, v33, v225, v71
	s_waitcnt vmcnt(31)
	v_mul_f32_e32 v226, 0x3fb8aa3b, v226
	v_exp_f32_e32 v226, v226
	v_cvt_pk_bf16_f32 v42, v30, v31
	v_cvt_pk_bf16_f32 v43, v32, v33
	global_store_dwordx2 v6, v[42:43], s[98:99]
	s_add_u32 s98, s98, 0x40000
	s_addc_u32 s99, s99, 0
	v_fma_f32 v30, v30, v226, v72
	v_fma_f32 v31, v31, v226, v73
	v_fma_f32 v32, v32, v226, v74
	v_fma_f32 v33, v33, v226, v75
	s_waitcnt vmcnt(31)
	v_mul_f32_e32 v227, 0x3fb8aa3b, v227
	v_exp_f32_e32 v227, v227
	v_cvt_pk_bf16_f32 v42, v30, v31
	v_cvt_pk_bf16_f32 v43, v32, v33
	global_store_dwordx2 v6, v[42:43], s[98:99]
	s_add_u32 s98, s98, 0x40000
	s_addc_u32 s99, s99, 0
	v_fma_f32 v30, v30, v227, v76
	v_fma_f32 v31, v31, v227, v77
	v_fma_f32 v32, v32, v227, v78
	v_fma_f32 v33, v33, v227, v79
	s_waitcnt vmcnt(31)
	v_mul_f32_e32 v228, 0x3fb8aa3b, v228
	v_exp_f32_e32 v228, v228
	v_cvt_pk_bf16_f32 v42, v30, v31
	v_cvt_pk_bf16_f32 v43, v32, v33
	global_store_dwordx2 v6, v[42:43], s[98:99]
	s_add_u32 s98, s98, 0x40000
	s_addc_u32 s99, s99, 0
	v_fma_f32 v30, v30, v228, v80
	v_fma_f32 v31, v31, v228, v81
	v_fma_f32 v32, v32, v228, v82
	v_fma_f32 v33, v33, v228, v83
	s_waitcnt vmcnt(31)
	v_mul_f32_e32 v229, 0x3fb8aa3b, v229
	v_exp_f32_e32 v229, v229
	v_cvt_pk_bf16_f32 v42, v30, v31
	v_cvt_pk_bf16_f32 v43, v32, v33
	global_store_dwordx2 v6, v[42:43], s[98:99]
	s_add_u32 s98, s98, 0x40000
	s_addc_u32 s99, s99, 0
	v_fma_f32 v30, v30, v229, v84
	v_fma_f32 v31, v31, v229, v85
	v_fma_f32 v32, v32, v229, v86
	v_fma_f32 v33, v33, v229, v87
	s_waitcnt vmcnt(31)
	v_mul_f32_e32 v230, 0x3fb8aa3b, v230
	v_exp_f32_e32 v230, v230
	v_cvt_pk_bf16_f32 v42, v30, v31
	v_cvt_pk_bf16_f32 v43, v32, v33
	global_store_dwordx2 v6, v[42:43], s[98:99]
	s_add_u32 s98, s98, 0x40000
	s_addc_u32 s99, s99, 0
	v_fma_f32 v30, v30, v230, v88
	v_fma_f32 v31, v31, v230, v89
	v_fma_f32 v32, v32, v230, v90
	v_fma_f32 v33, v33, v230, v91
	s_waitcnt vmcnt(31)
	v_mul_f32_e32 v231, 0x3fb8aa3b, v231
	v_exp_f32_e32 v231, v231
	v_cvt_pk_bf16_f32 v42, v30, v31
	v_cvt_pk_bf16_f32 v43, v32, v33
	global_store_dwordx2 v6, v[42:43], s[98:99]
	s_add_u32 s98, s98, 0x40000
	s_addc_u32 s99, s99, 0
	v_fma_f32 v30, v30, v231, v92
	v_fma_f32 v31, v31, v231, v93
	v_fma_f32 v32, v32, v231, v94
	v_fma_f32 v33, v33, v231, v95
	s_waitcnt vmcnt(31)
	v_mul_f32_e32 v232, 0x3fb8aa3b, v232
	v_exp_f32_e32 v232, v232
	v_cvt_pk_bf16_f32 v42, v30, v31
	v_cvt_pk_bf16_f32 v43, v32, v33
	global_store_dwordx2 v6, v[42:43], s[98:99]
	s_add_u32 s98, s98, 0x40000
	s_addc_u32 s99, s99, 0
	v_fma_f32 v30, v30, v232, v96
	v_fma_f32 v31, v31, v232, v97
	v_fma_f32 v32, v32, v232, v98
	v_fma_f32 v33, v33, v232, v99
	s_waitcnt vmcnt(31)
	v_mul_f32_e32 v233, 0x3fb8aa3b, v233
	v_exp_f32_e32 v233, v233
	v_cvt_pk_bf16_f32 v42, v30, v31
	v_cvt_pk_bf16_f32 v43, v32, v33
	global_store_dwordx2 v6, v[42:43], s[98:99]
	s_add_u32 s98, s98, 0x40000
	s_addc_u32 s99, s99, 0
	v_fma_f32 v30, v30, v233, v100
	v_fma_f32 v31, v31, v233, v101
	v_fma_f32 v32, v32, v233, v102
	v_fma_f32 v33, v33, v233, v103
	s_waitcnt vmcnt(31)
	v_mul_f32_e32 v234, 0x3fb8aa3b, v234
	v_exp_f32_e32 v234, v234
	v_cvt_pk_bf16_f32 v42, v30, v31
	v_cvt_pk_bf16_f32 v43, v32, v33
	global_store_dwordx2 v6, v[42:43], s[98:99]
	s_add_u32 s98, s98, 0x40000
	s_addc_u32 s99, s99, 0
	v_fma_f32 v30, v30, v234, v104
	v_fma_f32 v31, v31, v234, v105
	v_fma_f32 v32, v32, v234, v106
	v_fma_f32 v33, v33, v234, v107
	s_waitcnt vmcnt(31)
	v_mul_f32_e32 v235, 0x3fb8aa3b, v235
	v_exp_f32_e32 v235, v235
	v_cvt_pk_bf16_f32 v42, v30, v31
	v_cvt_pk_bf16_f32 v43, v32, v33
	global_store_dwordx2 v6, v[42:43], s[98:99]
	s_add_u32 s98, s98, 0x40000
	s_addc_u32 s99, s99, 0
	v_fma_f32 v30, v30, v235, v108
	v_fma_f32 v31, v31, v235, v109
	v_fma_f32 v32, v32, v235, v110
	v_fma_f32 v33, v33, v235, v111
	s_waitcnt vmcnt(31)
	v_mul_f32_e32 v236, 0x3fb8aa3b, v236
	v_exp_f32_e32 v236, v236
	v_cvt_pk_bf16_f32 v42, v30, v31
	v_cvt_pk_bf16_f32 v43, v32, v33
	global_store_dwordx2 v6, v[42:43], s[98:99]
	s_add_u32 s98, s98, 0x40000
	s_addc_u32 s99, s99, 0
	v_fma_f32 v30, v30, v236, v112
	v_fma_f32 v31, v31, v236, v113
	v_fma_f32 v32, v32, v236, v114
	v_fma_f32 v33, v33, v236, v115
	s_waitcnt vmcnt(31)
; DI unsigned pk2(float lo, float hi) { unsigned r; asm volatile("v_cvt_pk_bf16_f32 %0, %1, %2" : "=v"(r) : "v"(lo), "v"(hi)); return r; }
; DI void scan_unit(const Params& p, int hf, int su, int tid) {
;     ...
; #pragma unroll 8
;       for (int c = 0; c < 64; ++c) {
;         const float4 lo = *(const float4*)(ptr + (size_t)c * 16 * 8192);
;         uint2 w; w.x = pk2(S0, S1); w.y = pk2(S2, S3); *(uint2*)(pp + (size_t)c * 16 * 8192) = w;
;         const float dc = __expf(asum[(bl * 64 + c) * 16 + h]);
;         S0 = S0 * dc + lo.x; S1 = S1 * dc + lo.y; S2 = S2 * dc + lo.z; S3 = S3 * dc + lo.w;
;       }
	v_mul_f32_e32 v237, 0x3fb8aa3b, v237
	v_exp_f32_e32 v237, v237
	v_cvt_pk_bf16_f32 v42, v30, v31
	v_cvt_pk_bf16_f32 v43, v32, v33
	global_store_dwordx2 v6, v[42:43], s[98:99]
	s_add_u32 s98, s98, 0x40000
	s_addc_u32 s99, s99, 0
	v_fma_f32 v30, v30, v237, v116
	v_fma_f32 v31, v31, v237, v117
	v_fma_f32 v32, v32, v237, v118
	v_fma_f32 v33, v33, v237, v119
	s_waitcnt vmcnt(31)
	v_mul_f32_e32 v238, 0x3fb8aa3b, v238
	v_exp_f32_e32 v238, v238
	v_cvt_pk_bf16_f32 v42, v30, v31
	v_cvt_pk_bf16_f32 v43, v32, v33
	global_store_dwordx2 v6, v[42:43], s[98:99]
	s_add_u32 s98, s98, 0x40000
	s_addc_u32 s99, s99, 0
	v_fma_f32 v30, v30, v238, v120
	v_fma_f32 v31, v31, v238, v121
	v_fma_f32 v32, v32, v238, v122
	v_fma_f32 v33, v33, v238, v123
	s_waitcnt vmcnt(31)
	v_mul_f32_e32 v239, 0x3fb8aa3b, v239
	v_exp_f32_e32 v239, v239
	v_cvt_pk_bf16_f32 v42, v30, v31
	v_cvt_pk_bf16_f32 v43, v32, v33
	global_store_dwordx2 v6, v[42:43], s[98:99]
	s_add_u32 s98, s98, 0x40000
	s_addc_u32 s99, s99, 0
	v_fma_f32 v30, v30, v239, v124
	v_fma_f32 v31, v31, v239, v125
	v_fma_f32 v32, v32, v239, v126
	v_fma_f32 v33, v33, v239, v127
	s_waitcnt vmcnt(31)
	v_mul_f32_e32 v240, 0x3fb8aa3b, v240
	v_exp_f32_e32 v240, v240
	v_cvt_pk_bf16_f32 v42, v30, v31
	v_cvt_pk_bf16_f32 v43, v32, v33
	global_store_dwordx2 v6, v[42:43], s[98:99]
	s_add_u32 s98, s98, 0x40000
	s_addc_u32 s99, s99, 0
	v_fma_f32 v30, v30, v240, v128
	v_fma_f32 v31, v31, v240, v129
	v_fma_f32 v32, v32, v240, v130
	v_fma_f32 v33, v33, v240, v131
	s_waitcnt vmcnt(31)
	v_mul_f32_e32 v241, 0x3fb8aa3b, v241
	v_exp_f32_e32 v241, v241
	v_cvt_pk_bf16_f32 v42, v30, v31
	v_cvt_pk_bf16_f32 v43, v32, v33
	global_store_dwordx2 v6, v[42:43], s[98:99]
	s_add_u32 s98, s98, 0x40000
	s_addc_u32 s99, s99, 0
	v_fma_f32 v30, v30, v241, v132
	v_fma_f32 v31, v31, v241, v133
	v_fma_f32 v32, v32, v241, v134
	v_fma_f32 v33, v33, v241, v135
	s_waitcnt vmcnt(31)
	v_mul_f32_e32 v242, 0x3fb8aa3b, v242
	v_exp_f32_e32 v242, v242
	v_cvt_pk_bf16_f32 v42, v30, v31
	v_cvt_pk_bf16_f32 v43, v32, v33
	global_store_dwordx2 v6, v[42:43], s[98:99]
	s_add_u32 s98, s98, 0x40000
	s_addc_u32 s99, s99, 0
	v_fma_f32 v30, v30, v242, v136
	v_fma_f32 v31, v31, v242, v137
	v_fma_f32 v32, v32, v242, v138
	v_fma_f32 v33, v33, v242, v139
	s_waitcnt vmcnt(31)
	v_mul_f32_e32 v243, 0x3fb8aa3b, v243
	v_exp_f32_e32 v243, v243
	v_cvt_pk_bf16_f32 v42, v30, v31
	v_cvt_pk_bf16_f32 v43, v32, v33
	global_store_dwordx2 v6, v[42:43], s[98:99]
	s_add_u32 s98, s98, 0x40000
	s_addc_u32 s99, s99, 0
	v_fma_f32 v30, v30, v243, v140
	v_fma_f32 v31, v31, v243, v141
	v_fma_f32 v32, v32, v243, v142
	v_fma_f32 v33, v33, v243, v143
	s_waitcnt vmcnt(31)
	v_mul_f32_e32 v244, 0x3fb8aa3b, v244
	v_exp_f32_e32 v244, v244
	v_cvt_pk_bf16_f32 v42, v30, v31
	v_cvt_pk_bf16_f32 v43, v32, v33
	global_store_dwordx2 v6, v[42:43], s[98:99]
	s_add_u32 s98, s98, 0x40000
	s_addc_u32 s99, s99, 0
	v_fma_f32 v30, v30, v244, v144
	v_fma_f32 v31, v31, v244, v145
	v_fma_f32 v32, v32, v244, v146
	v_fma_f32 v33, v33, v244, v147
	s_waitcnt vmcnt(31)
	v_mul_f32_e32 v245, 0x3fb8aa3b, v245
	v_exp_f32_e32 v245, v245
	v_cvt_pk_bf16_f32 v42, v30, v31
	v_cvt_pk_bf16_f32 v43, v32, v33
	global_store_dwordx2 v6, v[42:43], s[98:99]
	s_add_u32 s98, s98, 0x40000
	s_addc_u32 s99, s99, 0
	v_fma_f32 v30, v30, v245, v148
	v_fma_f32 v31, v31, v245, v149
	v_fma_f32 v32, v32, v245, v150
	v_fma_f32 v33, v33, v245, v151
	s_waitcnt vmcnt(31)
	v_mul_f32_e32 v246, 0x3fb8aa3b, v246
	v_exp_f32_e32 v246, v246
	v_cvt_pk_bf16_f32 v42, v30, v31
	v_cvt_pk_bf16_f32 v43, v32, v33
	global_store_dwordx2 v6, v[42:43], s[98:99]
	s_add_u32 s98, s98, 0x40000
	s_addc_u32 s99, s99, 0
	v_fma_f32 v30, v30, v246, v152
	v_fma_f32 v31, v31, v246, v153
	v_fma_f32 v32, v32, v246, v154
	v_fma_f32 v33, v33, v246, v155
	s_waitcnt vmcnt(31)
	v_mul_f32_e32 v247, 0x3fb8aa3b, v247
	v_exp_f32_e32 v247, v247
	v_cvt_pk_bf16_f32 v42, v30, v31
	v_cvt_pk_bf16_f32 v43, v32, v33
	global_store_dwordx2 v6, v[42:43], s[98:99]
	s_add_u32 s98, s98, 0x40000
	s_addc_u32 s99, s99, 0
	v_fma_f32 v30, v30, v247, v156
	v_fma_f32 v31, v31, v247, v157
	v_fma_f32 v32, v32, v247, v158
	v_fma_f32 v33, v33, v247, v159
	s_waitcnt vmcnt(31)
	v_mul_f32_e32 v248, 0x3fb8aa3b, v248
	v_exp_f32_e32 v248, v248
	v_cvt_pk_bf16_f32 v42, v30, v31
	v_cvt_pk_bf16_f32 v43, v32, v33
	global_store_dwordx2 v6, v[42:43], s[98:99]
	s_add_u32 s98, s98, 0x40000
	s_addc_u32 s99, s99, 0
	v_fma_f32 v30, v30, v248, v204
	v_fma_f32 v31, v31, v248, v205
	v_fma_f32 v32, v32, v248, v206
	v_fma_f32 v33, v33, v248, v207
	s_waitcnt vmcnt(31)
	v_mul_f32_e32 v249, 0x3fb8aa3b, v249
	v_exp_f32_e32 v249, v249
	v_cvt_pk_bf16_f32 v42, v30, v31
	v_cvt_pk_bf16_f32 v43, v32, v33
	global_store_dwordx2 v6, v[42:43], s[98:99]
	s_add_u32 s98, s98, 0x40000
	s_addc_u32 s99, s99, 0
	v_fma_f32 v30, v30, v249, v208
	v_fma_f32 v31, v31, v249, v209
	v_fma_f32 v32, v32, v249, v210
	v_fma_f32 v33, v33, v249, v211
	s_waitcnt vmcnt(31)
	v_mul_f32_e32 v250, 0x3fb8aa3b, v250
	v_exp_f32_e32 v250, v250
	v_cvt_pk_bf16_f32 v42, v30, v31
	v_cvt_pk_bf16_f32 v43, v32, v33
	global_store_dwordx2 v6, v[42:43], s[98:99]
	s_add_u32 s98, s98, 0x40000
	s_addc_u32 s99, s99, 0
	v_fma_f32 v30, v30, v250, v212
	v_fma_f32 v31, v31, v250, v213
	v_fma_f32 v32, v32, v250, v214
	v_fma_f32 v33, v33, v250, v215
	s_waitcnt vmcnt(31)
; DI unsigned pk2(float lo, float hi) { unsigned r; asm volatile("v_cvt_pk_bf16_f32 %0, %1, %2" : "=v"(r) : "v"(lo), "v"(hi)); return r; }
; DI void scan_unit(const Params& p, int hf, int su, int tid) {
;     ...
; #pragma unroll 8
;       for (int c = 0; c < 64; ++c) {
;         const float4 lo = *(const float4*)(ptr + (size_t)c * 16 * 8192);
;         uint2 w; w.x = pk2(S0, S1); w.y = pk2(S2, S3); *(uint2*)(pp + (size_t)c * 16 * 8192) = w;
;         const float dc = __expf(asum[(bl * 64 + c) * 16 + h]);
;         S0 = S0 * dc + lo.x; S1 = S1 * dc + lo.y; S2 = S2 * dc + lo.z; S3 = S3 * dc + lo.w;
;       }
	v_mul_f32_e32 v251, 0x3fb8aa3b, v251
	v_exp_f32_e32 v251, v251
	v_cvt_pk_bf16_f32 v42, v30, v31
	v_cvt_pk_bf16_f32 v43, v32, v33
	global_store_dwordx2 v6, v[42:43], s[98:99]
	s_add_u32 s98, s98, 0x40000
	s_addc_u32 s99, s99, 0
	v_fma_f32 v30, v30, v251, v216
	v_fma_f32 v31, v31, v251, v217
	v_fma_f32 v32, v32, v251, v218
	v_fma_f32 v33, v33, v251, v219
	global_load_dwordx4 v[48:51], v8, s[8:9]
	s_add_u32 s8, s8, 0x80000
	s_addc_u32 s9, s9, 0
	global_load_dwordx4 v[52:55], v8, s[8:9]
	s_add_u32 s8, s8, 0x80000
	s_addc_u32 s9, s9, 0
	global_load_dwordx4 v[56:59], v8, s[8:9]
	s_add_u32 s8, s8, 0x80000
	s_addc_u32 s9, s9, 0
	global_load_dwordx4 v[60:63], v8, s[8:9]
	s_add_u32 s8, s8, 0x80000
	s_addc_u32 s9, s9, 0
	global_load_dwordx4 v[64:67], v8, s[8:9]
	s_add_u32 s8, s8, 0x80000
	s_addc_u32 s9, s9, 0
	global_load_dwordx4 v[68:71], v8, s[8:9]
	s_add_u32 s8, s8, 0x80000
	s_addc_u32 s9, s9, 0
	global_load_dwordx4 v[72:75], v8, s[8:9]
	s_add_u32 s8, s8, 0x80000
	s_addc_u32 s9, s9, 0
	global_load_dwordx4 v[76:79], v8, s[8:9]
	s_add_u32 s8, s8, 0x80000
	s_addc_u32 s9, s9, 0
	global_load_dwordx4 v[80:83], v8, s[8:9]
	s_add_u32 s8, s8, 0x80000
	s_addc_u32 s9, s9, 0
	global_load_dwordx4 v[84:87], v8, s[8:9]
	s_add_u32 s8, s8, 0x80000
	s_addc_u32 s9, s9, 0
	global_load_dwordx4 v[88:91], v8, s[8:9]
	s_add_u32 s8, s8, 0x80000
	s_addc_u32 s9, s9, 0
	global_load_dwordx4 v[92:95], v8, s[8:9]
	s_add_u32 s8, s8, 0x80000
	s_addc_u32 s9, s9, 0
	global_load_dwordx4 v[96:99], v8, s[8:9]
	s_add_u32 s8, s8, 0x80000
	s_addc_u32 s9, s9, 0
	global_load_dwordx4 v[100:103], v8, s[8:9]
	s_add_u32 s8, s8, 0x80000
	s_addc_u32 s9, s9, 0
	global_load_dwordx4 v[104:107], v8, s[8:9]
	s_add_u32 s8, s8, 0x80000
	s_addc_u32 s9, s9, 0
	global_load_dwordx4 v[108:111], v8, s[8:9]
	s_add_u32 s8, s8, 0x80000
	s_addc_u32 s9, s9, 0
	global_load_dwordx4 v[112:115], v8, s[8:9]
	s_add_u32 s8, s8, 0x80000
	s_addc_u32 s9, s9, 0
	global_load_dwordx4 v[116:119], v8, s[8:9]
	s_add_u32 s8, s8, 0x80000
	s_addc_u32 s9, s9, 0
	global_load_dwordx4 v[120:123], v8, s[8:9]
	s_add_u32 s8, s8, 0x80000
	s_addc_u32 s9, s9, 0
	global_load_dwordx4 v[124:127], v8, s[8:9]
	s_add_u32 s8, s8, 0x80000
	s_addc_u32 s9, s9, 0
	global_load_dwordx4 v[128:131], v8, s[8:9]
	s_add_u32 s8, s8, 0x80000
	s_addc_u32 s9, s9, 0
	global_load_dwordx4 v[132:135], v8, s[8:9]
	s_add_u32 s8, s8, 0x80000
	s_addc_u32 s9, s9, 0
	global_load_dwordx4 v[136:139], v8, s[8:9]
	s_add_u32 s8, s8, 0x80000
	s_addc_u32 s9, s9, 0
	global_load_dwordx4 v[140:143], v8, s[8:9]
	s_add_u32 s8, s8, 0x80000
	s_addc_u32 s9, s9, 0
	global_load_dwordx4 v[144:147], v8, s[8:9]
	s_add_u32 s8, s8, 0x80000
	s_addc_u32 s9, s9, 0
	global_load_dwordx4 v[148:151], v8, s[8:9]
	s_add_u32 s8, s8, 0x80000
	s_addc_u32 s9, s9, 0
	global_load_dwordx4 v[152:155], v8, s[8:9]
	s_add_u32 s8, s8, 0x80000
	s_addc_u32 s9, s9, 0
	global_load_dwordx4 v[156:159], v8, s[8:9]
	s_add_u32 s8, s8, 0x80000
	s_addc_u32 s9, s9, 0
	global_load_dwordx4 v[204:207], v8, s[8:9]
	s_add_u32 s8, s8, 0x80000
	s_addc_u32 s9, s9, 0
	global_load_dwordx4 v[208:211], v8, s[8:9]
	s_add_u32 s8, s8, 0x80000
	s_addc_u32 s9, s9, 0
	global_load_dwordx4 v[212:215], v8, s[8:9]
	s_add_u32 s8, s8, 0x80000
	s_addc_u32 s9, s9, 0
	global_load_dwordx4 v[216:219], v8, s[8:9]
	s_add_u32 s8, s8, 0x80000
	s_addc_u32 s9, s9, 0
	global_load_dword v220, v24, s[10:11]
	global_load_dword v221, v24, s[10:11] offset:64
	global_load_dword v222, v24, s[10:11] offset:128
	global_load_dword v223, v24, s[10:11] offset:192
	global_load_dword v224, v24, s[10:11] offset:256
	global_load_dword v225, v24, s[10:11] offset:320
	global_load_dword v226, v24, s[10:11] offset:384
	global_load_dword v227, v24, s[10:11] offset:448
	global_load_dword v228, v24, s[10:11] offset:512
	global_load_dword v229, v24, s[10:11] offset:576
	global_load_dword v230, v24, s[10:11] offset:640
	global_load_dword v231, v24, s[10:11] offset:704
	global_load_dword v232, v24, s[10:11] offset:768
	global_load_dword v233, v24, s[10:11] offset:832
	global_load_dword v234, v24, s[10:11] offset:896
	global_load_dword v235, v24, s[10:11] offset:960
	global_load_dword v236, v24, s[10:11] offset:1024
	global_load_dword v237, v24, s[10:11] offset:1088
	global_load_dword v238, v24, s[10:11] offset:1152
	global_load_dword v239, v24, s[10:11] offset:1216
	global_load_dword v240, v24, s[10:11] offset:1280
	global_load_dword v241, v24, s[10:11] offset:1344
	global_load_dword v242, v24, s[10:11] offset:1408
	global_load_dword v243, v24, s[10:11] offset:1472
	global_load_dword v244, v24, s[10:11] offset:1536
	global_load_dword v245, v24, s[10:11] offset:1600
	global_load_dword v246, v24, s[10:11] offset:1664
	global_load_dword v247, v24, s[10:11] offset:1728
	global_load_dword v248, v24, s[10:11] offset:1792
	global_load_dword v249, v24, s[10:11] offset:1856
	global_load_dword v250, v24, s[10:11] offset:1920
	global_load_dword v251, v24, s[10:11] offset:1984
	s_add_u32 s10, s10, 0x800
	s_addc_u32 s11, s11, 0
	s_waitcnt vmcnt(31)
	v_mul_f32_e32 v220, 0x3fb8aa3b, v220
	v_exp_f32_e32 v220, v220
	v_cvt_pk_bf16_f32 v42, v30, v31
	v_cvt_pk_bf16_f32 v43, v32, v33
	global_store_dwordx2 v6, v[42:43], s[98:99]
	s_add_u32 s98, s98, 0x40000
	s_addc_u32 s99, s99, 0
	v_fma_f32 v30, v30, v220, v48
	v_fma_f32 v31, v31, v220, v49
	v_fma_f32 v32, v32, v220, v50
	v_fma_f32 v33, v33, v220, v51
	s_waitcnt vmcnt(31)
	v_mul_f32_e32 v221, 0x3fb8aa3b, v221
	v_exp_f32_e32 v221, v221
	v_cvt_pk_bf16_f32 v42, v30, v31
	v_cvt_pk_bf16_f32 v43, v32, v33
	global_store_dwordx2 v6, v[42:43], s[98:99]
	s_add_u32 s98, s98, 0x40000
	s_addc_u32 s99, s99, 0
	v_fma_f32 v30, v30, v221, v52
	v_fma_f32 v31, v31, v221, v53
	v_fma_f32 v32, v32, v221, v54
	v_fma_f32 v33, v33, v221, v55
	s_waitcnt vmcnt(31)
; DI unsigned pk2(float lo, float hi) { unsigned r; asm volatile("v_cvt_pk_bf16_f32 %0, %1, %2" : "=v"(r) : "v"(lo), "v"(hi)); return r; }
; DI void scan_unit(const Params& p, int hf, int su, int tid) {
;     ...
; #pragma unroll 8
;       for (int c = 0; c < 64; ++c) {
;         const float4 lo = *(const float4*)(ptr + (size_t)c * 16 * 8192);
;         uint2 w; w.x = pk2(S0, S1); w.y = pk2(S2, S3); *(uint2*)(pp + (size_t)c * 16 * 8192) = w;
;         const float dc = __expf(asum[(bl * 64 + c) * 16 + h]);
;         S0 = S0 * dc + lo.x; S1 = S1 * dc + lo.y; S2 = S2 * dc + lo.z; S3 = S3 * dc + lo.w;
;       }
	v_mul_f32_e32 v222, 0x3fb8aa3b, v222
	v_exp_f32_e32 v222, v222
	v_cvt_pk_bf16_f32 v42, v30, v31
	v_cvt_pk_bf16_f32 v43, v32, v33
	global_store_dwordx2 v6, v[42:43], s[98:99]
	s_add_u32 s98, s98, 0x40000
	s_addc_u32 s99, s99, 0
	v_fma_f32 v30, v30, v222, v56
	v_fma_f32 v31, v31, v222, v57
	v_fma_f32 v32, v32, v222, v58
	v_fma_f32 v33, v33, v222, v59
	s_waitcnt vmcnt(31)
	v_mul_f32_e32 v223, 0x3fb8aa3b, v223
	v_exp_f32_e32 v223, v223
	v_cvt_pk_bf16_f32 v42, v30, v31
	v_cvt_pk_bf16_f32 v43, v32, v33
	global_store_dwordx2 v6, v[42:43], s[98:99]
	s_add_u32 s98, s98, 0x40000
	s_addc_u32 s99, s99, 0
	v_fma_f32 v30, v30, v223, v60
	v_fma_f32 v31, v31, v223, v61
	v_fma_f32 v32, v32, v223, v62
	v_fma_f32 v33, v33, v223, v63
	s_waitcnt vmcnt(31)
	v_mul_f32_e32 v224, 0x3fb8aa3b, v224
	v_exp_f32_e32 v224, v224
	v_cvt_pk_bf16_f32 v42, v30, v31
	v_cvt_pk_bf16_f32 v43, v32, v33
	global_store_dwordx2 v6, v[42:43], s[98:99]
	s_add_u32 s98, s98, 0x40000
	s_addc_u32 s99, s99, 0
	v_fma_f32 v30, v30, v224, v64
	v_fma_f32 v31, v31, v224, v65
	v_fma_f32 v32, v32, v224, v66
	v_fma_f32 v33, v33, v224, v67
	s_waitcnt vmcnt(31)
	v_mul_f32_e32 v225, 0x3fb8aa3b, v225
	v_exp_f32_e32 v225, v225
	v_cvt_pk_bf16_f32 v42, v30, v31
	v_cvt_pk_bf16_f32 v43, v32, v33
	global_store_dwordx2 v6, v[42:43], s[98:99]
	s_add_u32 s98, s98, 0x40000
	s_addc_u32 s99, s99, 0
	v_fma_f32 v30, v30, v225, v68
	v_fma_f32 v31, v31, v225, v69
	v_fma_f32 v32, v32, v225, v70
	v_fma_f32 v33, v33, v225, v71
	s_waitcnt vmcnt(31)
	v_mul_f32_e32 v226, 0x3fb8aa3b, v226
	v_exp_f32_e32 v226, v226
	v_cvt_pk_bf16_f32 v42, v30, v31
	v_cvt_pk_bf16_f32 v43, v32, v33
	global_store_dwordx2 v6, v[42:43], s[98:99]
	s_add_u32 s98, s98, 0x40000
	s_addc_u32 s99, s99, 0
	v_fma_f32 v30, v30, v226, v72
	v_fma_f32 v31, v31, v226, v73
	v_fma_f32 v32, v32, v226, v74
	v_fma_f32 v33, v33, v226, v75
	s_waitcnt vmcnt(31)
	v_mul_f32_e32 v227, 0x3fb8aa3b, v227
	v_exp_f32_e32 v227, v227
	v_cvt_pk_bf16_f32 v42, v30, v31
	v_cvt_pk_bf16_f32 v43, v32, v33
	global_store_dwordx2 v6, v[42:43], s[98:99]
	s_add_u32 s98, s98, 0x40000
	s_addc_u32 s99, s99, 0
	v_fma_f32 v30, v30, v227, v76
	v_fma_f32 v31, v31, v227, v77
	v_fma_f32 v32, v32, v227, v78
	v_fma_f32 v33, v33, v227, v79
	s_waitcnt vmcnt(31)
	v_mul_f32_e32 v228, 0x3fb8aa3b, v228
	v_exp_f32_e32 v228, v228
	v_cvt_pk_bf16_f32 v42, v30, v31
	v_cvt_pk_bf16_f32 v43, v32, v33
	global_store_dwordx2 v6, v[42:43], s[98:99]
	s_add_u32 s98, s98, 0x40000
	s_addc_u32 s99, s99, 0
	v_fma_f32 v30, v30, v228, v80
	v_fma_f32 v31, v31, v228, v81
	v_fma_f32 v32, v32, v228, v82
	v_fma_f32 v33, v33, v228, v83
	s_waitcnt vmcnt(31)
	v_mul_f32_e32 v229, 0x3fb8aa3b, v229
	v_exp_f32_e32 v229, v229
	v_cvt_pk_bf16_f32 v42, v30, v31
	v_cvt_pk_bf16_f32 v43, v32, v33
	global_store_dwordx2 v6, v[42:43], s[98:99]
	s_add_u32 s98, s98, 0x40000
	s_addc_u32 s99, s99, 0
	v_fma_f32 v30, v30, v229, v84
	v_fma_f32 v31, v31, v229, v85
	v_fma_f32 v32, v32, v229, v86
	v_fma_f32 v33, v33, v229, v87
	s_waitcnt vmcnt(31)
	v_mul_f32_e32 v230, 0x3fb8aa3b, v230
	v_exp_f32_e32 v230, v230
	v_cvt_pk_bf16_f32 v42, v30, v31
	v_cvt_pk_bf16_f32 v43, v32, v33
	global_store_dwordx2 v6, v[42:43], s[98:99]
	s_add_u32 s98, s98, 0x40000
	s_addc_u32 s99, s99, 0
	v_fma_f32 v30, v30, v230, v88
	v_fma_f32 v31, v31, v230, v89
	v_fma_f32 v32, v32, v230, v90
	v_fma_f32 v33, v33, v230, v91
	s_waitcnt vmcnt(31)
	v_mul_f32_e32 v231, 0x3fb8aa3b, v231
	v_exp_f32_e32 v231, v231
	v_cvt_pk_bf16_f32 v42, v30, v31
	v_cvt_pk_bf16_f32 v43, v32, v33
	global_store_dwordx2 v6, v[42:43], s[98:99]
	s_add_u32 s98, s98, 0x40000
	s_addc_u32 s99, s99, 0
	v_fma_f32 v30, v30, v231, v92
	v_fma_f32 v31, v31, v231, v93
	v_fma_f32 v32, v32, v231, v94
	v_fma_f32 v33, v33, v231, v95
	s_waitcnt vmcnt(31)
	v_mul_f32_e32 v232, 0x3fb8aa3b, v232
	v_exp_f32_e32 v232, v232
	v_cvt_pk_bf16_f32 v42, v30, v31
	v_cvt_pk_bf16_f32 v43, v32, v33
	global_store_dwordx2 v6, v[42:43], s[98:99]
	s_add_u32 s98, s98, 0x40000
	s_addc_u32 s99, s99, 0
	v_fma_f32 v30, v30, v232, v96
	v_fma_f32 v31, v31, v232, v97
	v_fma_f32 v32, v32, v232, v98
	v_fma_f32 v33, v33, v232, v99
	s_waitcnt vmcnt(31)
	v_mul_f32_e32 v233, 0x3fb8aa3b, v233
	v_exp_f32_e32 v233, v233
	v_cvt_pk_bf16_f32 v42, v30, v31
	v_cvt_pk_bf16_f32 v43, v32, v33
	global_store_dwordx2 v6, v[42:43], s[98:99]
	s_add_u32 s98, s98, 0x40000
	s_addc_u32 s99, s99, 0
	v_fma_f32 v30, v30, v233, v100
	v_fma_f32 v31, v31, v233, v101
	v_fma_f32 v32, v32, v233, v102
	v_fma_f32 v33, v33, v233, v103
	s_waitcnt vmcnt(31)
	v_mul_f32_e32 v234, 0x3fb8aa3b, v234
	v_exp_f32_e32 v234, v234
	v_cvt_pk_bf16_f32 v42, v30, v31
	v_cvt_pk_bf16_f32 v43, v32, v33
	global_store_dwordx2 v6, v[42:43], s[98:99]
	s_add_u32 s98, s98, 0x40000
	s_addc_u32 s99, s99, 0
	v_fma_f32 v30, v30, v234, v104
	v_fma_f32 v31, v31, v234, v105
	v_fma_f32 v32, v32, v234, v106
	v_fma_f32 v33, v33, v234, v107
	s_waitcnt vmcnt(31)
	v_mul_f32_e32 v235, 0x3fb8aa3b, v235
	v_exp_f32_e32 v235, v235
	v_cvt_pk_bf16_f32 v42, v30, v31
	v_cvt_pk_bf16_f32 v43, v32, v33
	global_store_dwordx2 v6, v[42:43], s[98:99]
	s_add_u32 s98, s98, 0x40000
	s_addc_u32 s99, s99, 0
	v_fma_f32 v30, v30, v235, v108
	v_fma_f32 v31, v31, v235, v109
	v_fma_f32 v32, v32, v235, v110
	v_fma_f32 v33, v33, v235, v111
	s_waitcnt vmcnt(31)
	v_mul_f32_e32 v236, 0x3fb8aa3b, v236
	v_exp_f32_e32 v236, v236
	v_cvt_pk_bf16_f32 v42, v30, v31
	v_cvt_pk_bf16_f32 v43, v32, v33
	global_store_dwordx2 v6, v[42:43], s[98:99]
	s_add_u32 s98, s98, 0x40000
	s_addc_u32 s99, s99, 0
	v_fma_f32 v30, v30, v236, v112
	v_fma_f32 v31, v31, v236, v113
	v_fma_f32 v32, v32, v236, v114
	v_fma_f32 v33, v33, v236, v115
	s_waitcnt vmcnt(31)
; DI unsigned pk2(float lo, float hi) { unsigned r; asm volatile("v_cvt_pk_bf16_f32 %0, %1, %2" : "=v"(r) : "v"(lo), "v"(hi)); return r; }
; DI void scan_unit(const Params& p, int hf, int su, int tid) {
;     ...
; #pragma unroll 8
;       for (int c = 0; c < 64; ++c) {
;         const float4 lo = *(const float4*)(ptr + (size_t)c * 16 * 8192);
;         uint2 w; w.x = pk2(S0, S1); w.y = pk2(S2, S3); *(uint2*)(pp + (size_t)c * 16 * 8192) = w;
;         const float dc = __expf(asum[(bl * 64 + c) * 16 + h]);
;         S0 = S0 * dc + lo.x; S1 = S1 * dc + lo.y; S2 = S2 * dc + lo.z; S3 = S3 * dc + lo.w;
;       }
	v_mul_f32_e32 v237, 0x3fb8aa3b, v237
	v_exp_f32_e32 v237, v237
	v_cvt_pk_bf16_f32 v42, v30, v31
	v_cvt_pk_bf16_f32 v43, v32, v33
	global_store_dwordx2 v6, v[42:43], s[98:99]
	s_add_u32 s98, s98, 0x40000
	s_addc_u32 s99, s99, 0
	v_fma_f32 v30, v30, v237, v116
	v_fma_f32 v31, v31, v237, v117
	v_fma_f32 v32, v32, v237, v118
	v_fma_f32 v33, v33, v237, v119
	s_waitcnt vmcnt(31)
	v_mul_f32_e32 v238, 0x3fb8aa3b, v238
	v_exp_f32_e32 v238, v238
	v_cvt_pk_bf16_f32 v42, v30, v31
	v_cvt_pk_bf16_f32 v43, v32, v33
	global_store_dwordx2 v6, v[42:43], s[98:99]
	s_add_u32 s98, s98, 0x40000
	s_addc_u32 s99, s99, 0
	v_fma_f32 v30, v30, v238, v120
	v_fma_f32 v31, v31, v238, v121
	v_fma_f32 v32, v32, v238, v122
	v_fma_f32 v33, v33, v238, v123
	s_waitcnt vmcnt(31)
	v_mul_f32_e32 v239, 0x3fb8aa3b, v239
	v_exp_f32_e32 v239, v239
	v_cvt_pk_bf16_f32 v42, v30, v31
	v_cvt_pk_bf16_f32 v43, v32, v33
	global_store_dwordx2 v6, v[42:43], s[98:99]
	s_add_u32 s98, s98, 0x40000
	s_addc_u32 s99, s99, 0
	v_fma_f32 v30, v30, v239, v124
	v_fma_f32 v31, v31, v239, v125
	v_fma_f32 v32, v32, v239, v126
	v_fma_f32 v33, v33, v239, v127
	s_waitcnt vmcnt(31)
	v_mul_f32_e32 v240, 0x3fb8aa3b, v240
	v_exp_f32_e32 v240, v240
	v_cvt_pk_bf16_f32 v42, v30, v31
	v_cvt_pk_bf16_f32 v43, v32, v33
	global_store_dwordx2 v6, v[42:43], s[98:99]
	s_add_u32 s98, s98, 0x40000
	s_addc_u32 s99, s99, 0
	v_fma_f32 v30, v30, v240, v128
	v_fma_f32 v31, v31, v240, v129
	v_fma_f32 v32, v32, v240, v130
	v_fma_f32 v33, v33, v240, v131
	s_waitcnt vmcnt(31)
	v_mul_f32_e32 v241, 0x3fb8aa3b, v241
	v_exp_f32_e32 v241, v241
	v_cvt_pk_bf16_f32 v42, v30, v31
	v_cvt_pk_bf16_f32 v43, v32, v33
	global_store_dwordx2 v6, v[42:43], s[98:99]
	s_add_u32 s98, s98, 0x40000
	s_addc_u32 s99, s99, 0
	v_fma_f32 v30, v30, v241, v132
	v_fma_f32 v31, v31, v241, v133
	v_fma_f32 v32, v32, v241, v134
	v_fma_f32 v33, v33, v241, v135
	s_waitcnt vmcnt(31)
	v_mul_f32_e32 v242, 0x3fb8aa3b, v242
	v_exp_f32_e32 v242, v242
	v_cvt_pk_bf16_f32 v42, v30, v31
	v_cvt_pk_bf16_f32 v43, v32, v33
	global_store_dwordx2 v6, v[42:43], s[98:99]
	s_add_u32 s98, s98, 0x40000
	s_addc_u32 s99, s99, 0
	v_fma_f32 v30, v30, v242, v136
	v_fma_f32 v31, v31, v242, v137
	v_fma_f32 v32, v32, v242, v138
	v_fma_f32 v33, v33, v242, v139
	s_waitcnt vmcnt(31)
	v_mul_f32_e32 v243, 0x3fb8aa3b, v243
	v_exp_f32_e32 v243, v243
	v_cvt_pk_bf16_f32 v42, v30, v31
	v_cvt_pk_bf16_f32 v43, v32, v33
	global_store_dwordx2 v6, v[42:43], s[98:99]
	s_add_u32 s98, s98, 0x40000
	s_addc_u32 s99, s99, 0
	v_fma_f32 v30, v30, v243, v140
	v_fma_f32 v31, v31, v243, v141
	v_fma_f32 v32, v32, v243, v142
	v_fma_f32 v33, v33, v243, v143
	s_waitcnt vmcnt(31)
	v_mul_f32_e32 v244, 0x3fb8aa3b, v244
	v_exp_f32_e32 v244, v244
	v_cvt_pk_bf16_f32 v42, v30, v31
	v_cvt_pk_bf16_f32 v43, v32, v33
	global_store_dwordx2 v6, v[42:43], s[98:99]
	s_add_u32 s98, s98, 0x40000
	s_addc_u32 s99, s99, 0
	v_fma_f32 v30, v30, v244, v144
	v_fma_f32 v31, v31, v244, v145
	v_fma_f32 v32, v32, v244, v146
	v_fma_f32 v33, v33, v244, v147
	s_waitcnt vmcnt(31)
	v_mul_f32_e32 v245, 0x3fb8aa3b, v245
	v_exp_f32_e32 v245, v245
	v_cvt_pk_bf16_f32 v42, v30, v31
	v_cvt_pk_bf16_f32 v43, v32, v33
	global_store_dwordx2 v6, v[42:43], s[98:99]
	s_add_u32 s98, s98, 0x40000
	s_addc_u32 s99, s99, 0
	v_fma_f32 v30, v30, v245, v148
	v_fma_f32 v31, v31, v245, v149
	v_fma_f32 v32, v32, v245, v150
	v_fma_f32 v33, v33, v245, v151
	s_waitcnt vmcnt(31)
	v_mul_f32_e32 v246, 0x3fb8aa3b, v246
	v_exp_f32_e32 v246, v246
	v_cvt_pk_bf16_f32 v42, v30, v31
	v_cvt_pk_bf16_f32 v43, v32, v33
	global_store_dwordx2 v6, v[42:43], s[98:99]
	s_add_u32 s98, s98, 0x40000
	s_addc_u32 s99, s99, 0
	v_fma_f32 v30, v30, v246, v152
	v_fma_f32 v31, v31, v246, v153
	v_fma_f32 v32, v32, v246, v154
	v_fma_f32 v33, v33, v246, v155
	s_waitcnt vmcnt(31)
	v_mul_f32_e32 v247, 0x3fb8aa3b, v247
	v_exp_f32_e32 v247, v247
	v_cvt_pk_bf16_f32 v42, v30, v31
	v_cvt_pk_bf16_f32 v43, v32, v33
	global_store_dwordx2 v6, v[42:43], s[98:99]
	s_add_u32 s98, s98, 0x40000
	s_addc_u32 s99, s99, 0
	v_fma_f32 v30, v30, v247, v156
	v_fma_f32 v31, v31, v247, v157
	v_fma_f32 v32, v32, v247, v158
	v_fma_f32 v33, v33, v247, v159
	s_waitcnt vmcnt(31)
	v_mul_f32_e32 v248, 0x3fb8aa3b, v248
	v_exp_f32_e32 v248, v248
	v_cvt_pk_bf16_f32 v42, v30, v31
	v_cvt_pk_bf16_f32 v43, v32, v33
	global_store_dwordx2 v6, v[42:43], s[98:99]
	s_add_u32 s98, s98, 0x40000
	s_addc_u32 s99, s99, 0
	v_fma_f32 v30, v30, v248, v204
	v_fma_f32 v31, v31, v248, v205
	v_fma_f32 v32, v32, v248, v206
	v_fma_f32 v33, v33, v248, v207
	s_waitcnt vmcnt(31)
	v_mul_f32_e32 v249, 0x3fb8aa3b, v249
	v_exp_f32_e32 v249, v249
	v_cvt_pk_bf16_f32 v42, v30, v31
	v_cvt_pk_bf16_f32 v43, v32, v33
	global_store_dwordx2 v6, v[42:43], s[98:99]
	s_add_u32 s98, s98, 0x40000
	s_addc_u32 s99, s99, 0
	v_fma_f32 v30, v30, v249, v208
	v_fma_f32 v31, v31, v249, v209
	v_fma_f32 v32, v32, v249, v210
	v_fma_f32 v33, v33, v249, v211
	s_waitcnt vmcnt(31)
	v_mul_f32_e32 v250, 0x3fb8aa3b, v250
	v_exp_f32_e32 v250, v250
	v_cvt_pk_bf16_f32 v42, v30, v31
	v_cvt_pk_bf16_f32 v43, v32, v33
	global_store_dwordx2 v6, v[42:43], s[98:99]
	s_add_u32 s98, s98, 0x40000
	s_addc_u32 s99, s99, 0
	v_fma_f32 v30, v30, v250, v212
	v_fma_f32 v31, v31, v250, v213
	v_fma_f32 v32, v32, v250, v214
	v_fma_f32 v33, v33, v250, v215
	s_waitcnt vmcnt(31)
	v_mul_f32_e32 v251, 0x3fb8aa3b, v251
	v_exp_f32_e32 v251, v251
	v_cvt_pk_bf16_f32 v42, v30, v31
	v_cvt_pk_bf16_f32 v43, v32, v33
	global_store_dwordx2 v6, v[42:43], s[98:99]
	s_add_u32 s98, s98, 0x40000
	s_addc_u32 s99, s99, 0
	v_fma_f32 v30, v30, v251, v216
	v_fma_f32 v31, v31, v251, v217
	v_fma_f32 v32, v32, v251, v218
	v_fma_f32 v33, v33, v251, v219

; DI unsigned pk2(float lo, float hi) { unsigned r; asm volatile("v_cvt_pk_bf16_f32 %0, %1, %2" : "=v"(r) : "v"(lo), "v"(hi)); return r; }
; DI float bflo(unsigned u) { return __uint_as_float(u << 16); }
; DI float bfhi(unsigned u) { return __uint_as_float(u & 0xffff0000u); }
; DI float ex2(float x) { return __builtin_amdgcn_exp2f(x); }
; DI void scan_unit(const Params& p, int hf, int su, int tid) {
;     ...
;     if (i < n_r) {
;       float S0 = 0.f, S1 = 0.f, S2 = 0.f, S3 = 0.f;
;       const int bl = i / 16384, hd = (i / 4096) & 3, e = (i & 4095) * 4;
;       const float dc = __expf(logf(1.0f - ex2(-5.0f - (float)hd)) * 128.0f);
;       bf16_t* ptr = rst + (size_t)(bl * 64 * 4 + hd) * 16384 + e;
; #pragma unroll 8
;       for (int c = 0; c < 64; ++c) {
;         uint2* q = (uint2*)(ptr + (size_t)c * 4 * 16384); const uint2 v = *q;
;         uint2 w; w.x = pk2(S0, S1); w.y = pk2(S2, S3); *q = w;
;         S0 = S0 * dc + bflo(v.x); S1 = S1 * dc + bfhi(v.x); S2 = S2 * dc + bflo(v.y); S3 = S3 * dc + bfhi(v.y);
;       }
.LBB0_582:
	v_subrev_u32_e32 v10, s38, v8
	s_add_u32 s8, s38, 0x15600000
	s_addc_u32 s9, s39, 0
	s_mov_b64 s[10:11], s[8:9]
	global_load_dwordx2 v[48:49], v10, s[8:9]
	s_add_u32 s8, s8, 0x20000
	s_addc_u32 s9, s9, 0
	global_load_dwordx2 v[50:51], v10, s[8:9]
	s_add_u32 s8, s8, 0x20000
	s_addc_u32 s9, s9, 0
	global_load_dwordx2 v[52:53], v10, s[8:9]
	s_add_u32 s8, s8, 0x20000
	s_addc_u32 s9, s9, 0
	global_load_dwordx2 v[54:55], v10, s[8:9]
	s_add_u32 s8, s8, 0x20000
	s_addc_u32 s9, s9, 0
	global_load_dwordx2 v[56:57], v10, s[8:9]
	s_add_u32 s8, s8, 0x20000
	s_addc_u32 s9, s9, 0
	global_load_dwordx2 v[58:59], v10, s[8:9]
	s_add_u32 s8, s8, 0x20000
	s_addc_u32 s9, s9, 0
	global_load_dwordx2 v[60:61], v10, s[8:9]
	s_add_u32 s8, s8, 0x20000
	s_addc_u32 s9, s9, 0
	global_load_dwordx2 v[62:63], v10, s[8:9]
	s_add_u32 s8, s8, 0x20000
	s_addc_u32 s9, s9, 0
	global_load_dwordx2 v[64:65], v10, s[8:9]
	s_add_u32 s8, s8, 0x20000
	s_addc_u32 s9, s9, 0
	global_load_dwordx2 v[66:67], v10, s[8:9]
	s_add_u32 s8, s8, 0x20000
	s_addc_u32 s9, s9, 0
	global_load_dwordx2 v[68:69], v10, s[8:9]
	s_add_u32 s8, s8, 0x20000
	s_addc_u32 s9, s9, 0
	global_load_dwordx2 v[70:71], v10, s[8:9]
	s_add_u32 s8, s8, 0x20000
	s_addc_u32 s9, s9, 0
	global_load_dwordx2 v[72:73], v10, s[8:9]
	s_add_u32 s8, s8, 0x20000
	s_addc_u32 s9, s9, 0
	global_load_dwordx2 v[74:75], v10, s[8:9]
	s_add_u32 s8, s8, 0x20000
	s_addc_u32 s9, s9, 0
	global_load_dwordx2 v[76:77], v10, s[8:9]
	s_add_u32 s8, s8, 0x20000
	s_addc_u32 s9, s9, 0
	global_load_dwordx2 v[78:79], v10, s[8:9]
	s_add_u32 s8, s8, 0x20000
	s_addc_u32 s9, s9, 0
	global_load_dwordx2 v[80:81], v10, s[8:9]
	s_add_u32 s8, s8, 0x20000
	s_addc_u32 s9, s9, 0
	global_load_dwordx2 v[82:83], v10, s[8:9]
	s_add_u32 s8, s8, 0x20000
	s_addc_u32 s9, s9, 0
	global_load_dwordx2 v[84:85], v10, s[8:9]
	s_add_u32 s8, s8, 0x20000
	s_addc_u32 s9, s9, 0
	global_load_dwordx2 v[86:87], v10, s[8:9]
	s_add_u32 s8, s8, 0x20000
	s_addc_u32 s9, s9, 0
	global_load_dwordx2 v[88:89], v10, s[8:9]
	s_add_u32 s8, s8, 0x20000
	s_addc_u32 s9, s9, 0
	global_load_dwordx2 v[90:91], v10, s[8:9]
	s_add_u32 s8, s8, 0x20000
	s_addc_u32 s9, s9, 0
	global_load_dwordx2 v[92:93], v10, s[8:9]
	s_add_u32 s8, s8, 0x20000
	s_addc_u32 s9, s9, 0
	global_load_dwordx2 v[94:95], v10, s[8:9]
	s_add_u32 s8, s8, 0x20000
	s_addc_u32 s9, s9, 0
	global_load_dwordx2 v[96:97], v10, s[8:9]
	s_add_u32 s8, s8, 0x20000
	s_addc_u32 s9, s9, 0
	global_load_dwordx2 v[98:99], v10, s[8:9]
	s_add_u32 s8, s8, 0x20000
	s_addc_u32 s9, s9, 0
	global_load_dwordx2 v[100:101], v10, s[8:9]
	s_add_u32 s8, s8, 0x20000
	s_addc_u32 s9, s9, 0
	global_load_dwordx2 v[102:103], v10, s[8:9]
	s_add_u32 s8, s8, 0x20000
	s_addc_u32 s9, s9, 0
	global_load_dwordx2 v[104:105], v10, s[8:9]
	s_add_u32 s8, s8, 0x20000
	s_addc_u32 s9, s9, 0
	global_load_dwordx2 v[106:107], v10, s[8:9]
	s_add_u32 s8, s8, 0x20000
	s_addc_u32 s9, s9, 0
	global_load_dwordx2 v[108:109], v10, s[8:9]
	s_add_u32 s8, s8, 0x20000
	s_addc_u32 s9, s9, 0
	global_load_dwordx2 v[110:111], v10, s[8:9]
	s_add_u32 s8, s8, 0x20000
	s_addc_u32 s9, s9, 0
	global_load_dwordx2 v[112:113], v10, s[8:9]
	s_add_u32 s8, s8, 0x20000
	s_addc_u32 s9, s9, 0
	global_load_dwordx2 v[114:115], v10, s[8:9]
	s_add_u32 s8, s8, 0x20000
	s_addc_u32 s9, s9, 0
	global_load_dwordx2 v[116:117], v10, s[8:9]
	s_add_u32 s8, s8, 0x20000
	s_addc_u32 s9, s9, 0
	global_load_dwordx2 v[118:119], v10, s[8:9]
	s_add_u32 s8, s8, 0x20000
	s_addc_u32 s9, s9, 0
	global_load_dwordx2 v[120:121], v10, s[8:9]
	s_add_u32 s8, s8, 0x20000
	s_addc_u32 s9, s9, 0
	global_load_dwordx2 v[122:123], v10, s[8:9]
	s_add_u32 s8, s8, 0x20000
	s_addc_u32 s9, s9, 0
	global_load_dwordx2 v[124:125], v10, s[8:9]
	s_add_u32 s8, s8, 0x20000
	s_addc_u32 s9, s9, 0
	global_load_dwordx2 v[126:127], v10, s[8:9]
	s_add_u32 s8, s8, 0x20000
	s_addc_u32 s9, s9, 0
	global_load_dwordx2 v[128:129], v10, s[8:9]
	s_add_u32 s8, s8, 0x20000
	s_addc_u32 s9, s9, 0
	global_load_dwordx2 v[130:131], v10, s[8:9]
	s_add_u32 s8, s8, 0x20000
	s_addc_u32 s9, s9, 0
	global_load_dwordx2 v[132:133], v10, s[8:9]
	s_add_u32 s8, s8, 0x20000
	s_addc_u32 s9, s9, 0
	global_load_dwordx2 v[134:135], v10, s[8:9]
	s_add_u32 s8, s8, 0x20000
	s_addc_u32 s9, s9, 0
	global_load_dwordx2 v[136:137], v10, s[8:9]
	s_add_u32 s8, s8, 0x20000
	s_addc_u32 s9, s9, 0
	global_load_dwordx2 v[138:139], v10, s[8:9]
	s_add_u32 s8, s8, 0x20000
	s_addc_u32 s9, s9, 0
	global_load_dwordx2 v[140:141], v10, s[8:9]
	s_add_u32 s8, s8, 0x20000
	s_addc_u32 s9, s9, 0
	global_load_dwordx2 v[142:143], v10, s[8:9]
	s_add_u32 s8, s8, 0x20000
	s_addc_u32 s9, s9, 0
	global_load_dwordx2 v[144:145], v10, s[8:9]
	s_add_u32 s8, s8, 0x20000
	s_addc_u32 s9, s9, 0
	global_load_dwordx2 v[146:147], v10, s[8:9]
	s_add_u32 s8, s8, 0x20000
	s_addc_u32 s9, s9, 0
	global_load_dwordx2 v[148:149], v10, s[8:9]
	s_add_u32 s8, s8, 0x20000
	s_addc_u32 s9, s9, 0
	global_load_dwordx2 v[150:151], v10, s[8:9]
	s_add_u32 s8, s8, 0x20000
	s_addc_u32 s9, s9, 0
	global_load_dwordx2 v[152:153], v10, s[8:9]
	s_add_u32 s8, s8, 0x20000
	s_addc_u32 s9, s9, 0
	global_load_dwordx2 v[154:155], v10, s[8:9]
	s_add_u32 s8, s8, 0x20000
	s_addc_u32 s9, s9, 0
	global_load_dwordx2 v[156:157], v10, s[8:9]
	s_add_u32 s8, s8, 0x20000
	s_addc_u32 s9, s9, 0
	global_load_dwordx2 v[158:159], v10, s[8:9]
	s_add_u32 s8, s8, 0x20000
	s_addc_u32 s9, s9, 0
	global_load_dwordx2 v[204:205], v10, s[8:9]
	s_add_u32 s8, s8, 0x20000
	s_addc_u32 s9, s9, 0
	global_load_dwordx2 v[206:207], v10, s[8:9]
	s_add_u32 s8, s8, 0x20000
	s_addc_u32 s9, s9, 0
	global_load_dwordx2 v[208:209], v10, s[8:9]
	s_add_u32 s8, s8, 0x20000
	s_addc_u32 s9, s9, 0
	global_load_dwordx2 v[210:211], v10, s[8:9]
	s_add_u32 s8, s8, 0x20000
	s_addc_u32 s9, s9, 0
	global_load_dwordx2 v[212:213], v10, s[8:9]
	s_add_u32 s8, s8, 0x20000
	s_addc_u32 s9, s9, 0
	global_load_dwordx2 v[214:215], v10, s[8:9]
	s_add_u32 s8, s8, 0x20000
	s_addc_u32 s9, s9, 0
	global_load_dwordx2 v[216:217], v10, s[8:9]
	s_add_u32 s8, s8, 0x20000
	s_addc_u32 s9, s9, 0
	global_load_dwordx2 v[218:219], v10, s[8:9]
	s_add_u32 s8, s8, 0x20000
	s_addc_u32 s9, s9, 0
	s_waitcnt vmcnt(63)
; DI unsigned pk2(float lo, float hi) { unsigned r; asm volatile("v_cvt_pk_bf16_f32 %0, %1, %2" : "=v"(r) : "v"(lo), "v"(hi)); return r; }
; DI float bflo(unsigned u) { return __uint_as_float(u << 16); }
; DI float bfhi(unsigned u) { return __uint_as_float(u & 0xffff0000u); }
; DI void scan_unit(const Params& p, int hf, int su, int tid) {
;     ...
; #pragma unroll 8
;       for (int c = 0; c < 64; ++c) {
;         uint2* q = (uint2*)(ptr + (size_t)c * 4 * 16384); const uint2 v = *q;
;         uint2 w; w.x = pk2(S0, S1); w.y = pk2(S2, S3); *q = w;
;         S0 = S0 * dc + bflo(v.x); S1 = S1 * dc + bfhi(v.x); S2 = S2 * dc + bflo(v.y); S3 = S3 * dc + bfhi(v.y);
;       }
	v_cvt_pk_bf16_f32 v20, v12, v13
	v_cvt_pk_bf16_f32 v21, v14, v15
	global_store_dwordx2 v10, v[20:21], s[10:11]
	s_add_u32 s10, s10, 0x20000
	s_addc_u32 s11, s11, 0
	v_lshlrev_b32_e32 v16, 16, v48
	v_and_b32_e32 v17, 0xffff0000, v48
	v_pk_fma_f32 v[12:13], v[6:7], v[12:13], v[16:17]
	v_lshlrev_b32_e32 v16, 16, v49
	v_and_b32_e32 v17, 0xffff0000, v49
	v_pk_fma_f32 v[14:15], v[6:7], v[14:15], v[16:17]
	s_waitcnt vmcnt(63)
	v_cvt_pk_bf16_f32 v20, v12, v13
	v_cvt_pk_bf16_f32 v21, v14, v15
	global_store_dwordx2 v10, v[20:21], s[10:11]
	s_add_u32 s10, s10, 0x20000
	s_addc_u32 s11, s11, 0
	v_lshlrev_b32_e32 v16, 16, v50
	v_and_b32_e32 v17, 0xffff0000, v50
	v_pk_fma_f32 v[12:13], v[6:7], v[12:13], v[16:17]
	v_lshlrev_b32_e32 v16, 16, v51
	v_and_b32_e32 v17, 0xffff0000, v51
	v_pk_fma_f32 v[14:15], v[6:7], v[14:15], v[16:17]
	s_waitcnt vmcnt(63)
	v_cvt_pk_bf16_f32 v20, v12, v13
	v_cvt_pk_bf16_f32 v21, v14, v15
	global_store_dwordx2 v10, v[20:21], s[10:11]
	s_add_u32 s10, s10, 0x20000
	s_addc_u32 s11, s11, 0
	v_lshlrev_b32_e32 v16, 16, v52
	v_and_b32_e32 v17, 0xffff0000, v52
	v_pk_fma_f32 v[12:13], v[6:7], v[12:13], v[16:17]
	v_lshlrev_b32_e32 v16, 16, v53
	v_and_b32_e32 v17, 0xffff0000, v53
	v_pk_fma_f32 v[14:15], v[6:7], v[14:15], v[16:17]
	s_waitcnt vmcnt(63)
	v_cvt_pk_bf16_f32 v20, v12, v13
	v_cvt_pk_bf16_f32 v21, v14, v15
	global_store_dwordx2 v10, v[20:21], s[10:11]
	s_add_u32 s10, s10, 0x20000
	s_addc_u32 s11, s11, 0
	v_lshlrev_b32_e32 v16, 16, v54
	v_and_b32_e32 v17, 0xffff0000, v54
	v_pk_fma_f32 v[12:13], v[6:7], v[12:13], v[16:17]
	v_lshlrev_b32_e32 v16, 16, v55
	v_and_b32_e32 v17, 0xffff0000, v55
	v_pk_fma_f32 v[14:15], v[6:7], v[14:15], v[16:17]
	s_waitcnt vmcnt(63)
	v_cvt_pk_bf16_f32 v20, v12, v13
	v_cvt_pk_bf16_f32 v21, v14, v15
	global_store_dwordx2 v10, v[20:21], s[10:11]
	s_add_u32 s10, s10, 0x20000
	s_addc_u32 s11, s11, 0
	v_lshlrev_b32_e32 v16, 16, v56
	v_and_b32_e32 v17, 0xffff0000, v56
	v_pk_fma_f32 v[12:13], v[6:7], v[12:13], v[16:17]
	v_lshlrev_b32_e32 v16, 16, v57
	v_and_b32_e32 v17, 0xffff0000, v57
	v_pk_fma_f32 v[14:15], v[6:7], v[14:15], v[16:17]
	s_waitcnt vmcnt(63)
	v_cvt_pk_bf16_f32 v20, v12, v13
	v_cvt_pk_bf16_f32 v21, v14, v15
	global_store_dwordx2 v10, v[20:21], s[10:11]
	s_add_u32 s10, s10, 0x20000
	s_addc_u32 s11, s11, 0
	v_lshlrev_b32_e32 v16, 16, v58
	v_and_b32_e32 v17, 0xffff0000, v58
	v_pk_fma_f32 v[12:13], v[6:7], v[12:13], v[16:17]
	v_lshlrev_b32_e32 v16, 16, v59
	v_and_b32_e32 v17, 0xffff0000, v59
	v_pk_fma_f32 v[14:15], v[6:7], v[14:15], v[16:17]
	s_waitcnt vmcnt(63)
	v_cvt_pk_bf16_f32 v20, v12, v13
	v_cvt_pk_bf16_f32 v21, v14, v15
	global_store_dwordx2 v10, v[20:21], s[10:11]
	s_add_u32 s10, s10, 0x20000
	s_addc_u32 s11, s11, 0
	v_lshlrev_b32_e32 v16, 16, v60
	v_and_b32_e32 v17, 0xffff0000, v60
	v_pk_fma_f32 v[12:13], v[6:7], v[12:13], v[16:17]
	v_lshlrev_b32_e32 v16, 16, v61
	v_and_b32_e32 v17, 0xffff0000, v61
	v_pk_fma_f32 v[14:15], v[6:7], v[14:15], v[16:17]
	s_waitcnt vmcnt(63)
	v_cvt_pk_bf16_f32 v20, v12, v13
	v_cvt_pk_bf16_f32 v21, v14, v15
	global_store_dwordx2 v10, v[20:21], s[10:11]
	s_add_u32 s10, s10, 0x20000
	s_addc_u32 s11, s11, 0
	v_lshlrev_b32_e32 v16, 16, v62
	v_and_b32_e32 v17, 0xffff0000, v62
	v_pk_fma_f32 v[12:13], v[6:7], v[12:13], v[16:17]
	v_lshlrev_b32_e32 v16, 16, v63
	v_and_b32_e32 v17, 0xffff0000, v63
	v_pk_fma_f32 v[14:15], v[6:7], v[14:15], v[16:17]
	s_waitcnt vmcnt(63)
	v_cvt_pk_bf16_f32 v20, v12, v13
	v_cvt_pk_bf16_f32 v21, v14, v15
	global_store_dwordx2 v10, v[20:21], s[10:11]
	s_add_u32 s10, s10, 0x20000
	s_addc_u32 s11, s11, 0
	v_lshlrev_b32_e32 v16, 16, v64
	v_and_b32_e32 v17, 0xffff0000, v64
	v_pk_fma_f32 v[12:13], v[6:7], v[12:13], v[16:17]
	v_lshlrev_b32_e32 v16, 16, v65
	v_and_b32_e32 v17, 0xffff0000, v65
	v_pk_fma_f32 v[14:15], v[6:7], v[14:15], v[16:17]
	s_waitcnt vmcnt(63)
	v_cvt_pk_bf16_f32 v20, v12, v13
	v_cvt_pk_bf16_f32 v21, v14, v15
	global_store_dwordx2 v10, v[20:21], s[10:11]
	s_add_u32 s10, s10, 0x20000
	s_addc_u32 s11, s11, 0
	v_lshlrev_b32_e32 v16, 16, v66
	v_and_b32_e32 v17, 0xffff0000, v66
	v_pk_fma_f32 v[12:13], v[6:7], v[12:13], v[16:17]
	v_lshlrev_b32_e32 v16, 16, v67
	v_and_b32_e32 v17, 0xffff0000, v67
	v_pk_fma_f32 v[14:15], v[6:7], v[14:15], v[16:17]
	s_waitcnt vmcnt(63)
	v_cvt_pk_bf16_f32 v20, v12, v13
	v_cvt_pk_bf16_f32 v21, v14, v15
	global_store_dwordx2 v10, v[20:21], s[10:11]
	s_add_u32 s10, s10, 0x20000
	s_addc_u32 s11, s11, 0
	v_lshlrev_b32_e32 v16, 16, v68
	v_and_b32_e32 v17, 0xffff0000, v68
	v_pk_fma_f32 v[12:13], v[6:7], v[12:13], v[16:17]
	v_lshlrev_b32_e32 v16, 16, v69
	v_and_b32_e32 v17, 0xffff0000, v69
	v_pk_fma_f32 v[14:15], v[6:7], v[14:15], v[16:17]
	s_waitcnt vmcnt(63)
	v_cvt_pk_bf16_f32 v20, v12, v13
	v_cvt_pk_bf16_f32 v21, v14, v15
	global_store_dwordx2 v10, v[20:21], s[10:11]
	s_add_u32 s10, s10, 0x20000
	s_addc_u32 s11, s11, 0
	v_lshlrev_b32_e32 v16, 16, v70
	v_and_b32_e32 v17, 0xffff0000, v70
	v_pk_fma_f32 v[12:13], v[6:7], v[12:13], v[16:17]
	v_lshlrev_b32_e32 v16, 16, v71
	v_and_b32_e32 v17, 0xffff0000, v71
	v_pk_fma_f32 v[14:15], v[6:7], v[14:15], v[16:17]
	s_waitcnt vmcnt(63)
	v_cvt_pk_bf16_f32 v20, v12, v13
	v_cvt_pk_bf16_f32 v21, v14, v15
	global_store_dwordx2 v10, v[20:21], s[10:11]
	s_add_u32 s10, s10, 0x20000
	s_addc_u32 s11, s11, 0
	v_lshlrev_b32_e32 v16, 16, v72
	v_and_b32_e32 v17, 0xffff0000, v72
	v_pk_fma_f32 v[12:13], v[6:7], v[12:13], v[16:17]
	v_lshlrev_b32_e32 v16, 16, v73
	v_and_b32_e32 v17, 0xffff0000, v73
	v_pk_fma_f32 v[14:15], v[6:7], v[14:15], v[16:17]
	s_waitcnt vmcnt(63)
; DI unsigned pk2(float lo, float hi) { unsigned r; asm volatile("v_cvt_pk_bf16_f32 %0, %1, %2" : "=v"(r) : "v"(lo), "v"(hi)); return r; }
; DI float bflo(unsigned u) { return __uint_as_float(u << 16); }
; DI float bfhi(unsigned u) { return __uint_as_float(u & 0xffff0000u); }
; DI float ex2(float x) { return __builtin_amdgcn_exp2f(x); }
; DI void scan_unit(const Params& p, int hf, int su, int tid) {
;     ...
;       float S0 = 0.f, S1 = 0.f, S2 = 0.f, S3 = 0.f;
;       const int bl = i / 16384, hd = (i / 4096) & 3, e = (i & 4095) * 4;
;       const float dc = __expf(logf(1.0f - ex2(-5.0f - (float)hd)) * 128.0f);
;       bf16_t* ptr = rst + (size_t)(bl * 64 * 4 + hd) * 16384 + e;
; #pragma unroll 8
;       for (int c = 0; c < 64; ++c) {
;         uint2* q = (uint2*)(ptr + (size_t)c * 4 * 16384); const uint2 v = *q;
;         uint2 w; w.x = pk2(S0, S1); w.y = pk2(S2, S3); *q = w;
;         S0 = S0 * dc + bflo(v.x); S1 = S1 * dc + bfhi(v.x); S2 = S2 * dc + bflo(v.y); S3 = S3 * dc + bfhi(v.y);
;       }
	v_cvt_pk_bf16_f32 v20, v12, v13
	v_cvt_pk_bf16_f32 v21, v14, v15
	global_store_dwordx2 v10, v[20:21], s[10:11]
	s_add_u32 s10, s10, 0x20000
	s_addc_u32 s11, s11, 0
	v_lshlrev_b32_e32 v16, 16, v74
	v_and_b32_e32 v17, 0xffff0000, v74
	v_pk_fma_f32 v[12:13], v[6:7], v[12:13], v[16:17]
	v_lshlrev_b32_e32 v16, 16, v75
	v_and_b32_e32 v17, 0xffff0000, v75
	v_pk_fma_f32 v[14:15], v[6:7], v[14:15], v[16:17]
	s_waitcnt vmcnt(63)
	v_cvt_pk_bf16_f32 v20, v12, v13
	v_cvt_pk_bf16_f32 v21, v14, v15
	global_store_dwordx2 v10, v[20:21], s[10:11]
	s_add_u32 s10, s10, 0x20000
	s_addc_u32 s11, s11, 0
	v_lshlrev_b32_e32 v16, 16, v76
	v_and_b32_e32 v17, 0xffff0000, v76
	v_pk_fma_f32 v[12:13], v[6:7], v[12:13], v[16:17]
	v_lshlrev_b32_e32 v16, 16, v77
	v_and_b32_e32 v17, 0xffff0000, v77
	v_pk_fma_f32 v[14:15], v[6:7], v[14:15], v[16:17]
	s_waitcnt vmcnt(63)
	v_cvt_pk_bf16_f32 v20, v12, v13
	v_cvt_pk_bf16_f32 v21, v14, v15
	global_store_dwordx2 v10, v[20:21], s[10:11]
	s_add_u32 s10, s10, 0x20000
	s_addc_u32 s11, s11, 0
	v_lshlrev_b32_e32 v16, 16, v78
	v_and_b32_e32 v17, 0xffff0000, v78
	v_pk_fma_f32 v[12:13], v[6:7], v[12:13], v[16:17]
	v_lshlrev_b32_e32 v16, 16, v79
	v_and_b32_e32 v17, 0xffff0000, v79
	v_pk_fma_f32 v[14:15], v[6:7], v[14:15], v[16:17]
	s_waitcnt vmcnt(63)
	v_cvt_pk_bf16_f32 v20, v12, v13
	v_cvt_pk_bf16_f32 v21, v14, v15
	global_store_dwordx2 v10, v[20:21], s[10:11]
	s_add_u32 s10, s10, 0x20000
	s_addc_u32 s11, s11, 0
	v_lshlrev_b32_e32 v16, 16, v80
	v_and_b32_e32 v17, 0xffff0000, v80
	v_pk_fma_f32 v[12:13], v[6:7], v[12:13], v[16:17]
	v_lshlrev_b32_e32 v16, 16, v81
	v_and_b32_e32 v17, 0xffff0000, v81
	v_pk_fma_f32 v[14:15], v[6:7], v[14:15], v[16:17]
	s_waitcnt vmcnt(63)
	v_cvt_pk_bf16_f32 v20, v12, v13
	v_cvt_pk_bf16_f32 v21, v14, v15
	global_store_dwordx2 v10, v[20:21], s[10:11]
	s_add_u32 s10, s10, 0x20000
	s_addc_u32 s11, s11, 0
	v_lshlrev_b32_e32 v16, 16, v82
	v_and_b32_e32 v17, 0xffff0000, v82
	v_pk_fma_f32 v[12:13], v[6:7], v[12:13], v[16:17]
	v_lshlrev_b32_e32 v16, 16, v83
	v_and_b32_e32 v17, 0xffff0000, v83
	v_pk_fma_f32 v[14:15], v[6:7], v[14:15], v[16:17]
	s_waitcnt vmcnt(63)
	v_cvt_pk_bf16_f32 v20, v12, v13
	v_cvt_pk_bf16_f32 v21, v14, v15
	global_store_dwordx2 v10, v[20:21], s[10:11]
	s_add_u32 s10, s10, 0x20000
	s_addc_u32 s11, s11, 0
	v_lshlrev_b32_e32 v16, 16, v84
	v_and_b32_e32 v17, 0xffff0000, v84
	v_pk_fma_f32 v[12:13], v[6:7], v[12:13], v[16:17]
	v_lshlrev_b32_e32 v16, 16, v85
	v_and_b32_e32 v17, 0xffff0000, v85
	v_pk_fma_f32 v[14:15], v[6:7], v[14:15], v[16:17]
	s_waitcnt vmcnt(63)
	v_cvt_pk_bf16_f32 v20, v12, v13
	v_cvt_pk_bf16_f32 v21, v14, v15
	global_store_dwordx2 v10, v[20:21], s[10:11]
	s_add_u32 s10, s10, 0x20000
	s_addc_u32 s11, s11, 0
	v_lshlrev_b32_e32 v16, 16, v86
	v_and_b32_e32 v17, 0xffff0000, v86
	v_pk_fma_f32 v[12:13], v[6:7], v[12:13], v[16:17]
	v_lshlrev_b32_e32 v16, 16, v87
	v_and_b32_e32 v17, 0xffff0000, v87
	v_pk_fma_f32 v[14:15], v[6:7], v[14:15], v[16:17]
	s_waitcnt vmcnt(63)
	v_cvt_pk_bf16_f32 v20, v12, v13
	v_cvt_pk_bf16_f32 v21, v14, v15
	global_store_dwordx2 v10, v[20:21], s[10:11]
	s_add_u32 s10, s10, 0x20000
	s_addc_u32 s11, s11, 0
	v_lshlrev_b32_e32 v16, 16, v88
	v_and_b32_e32 v17, 0xffff0000, v88
	v_pk_fma_f32 v[12:13], v[6:7], v[12:13], v[16:17]
	v_lshlrev_b32_e32 v16, 16, v89
	v_and_b32_e32 v17, 0xffff0000, v89
	v_pk_fma_f32 v[14:15], v[6:7], v[14:15], v[16:17]
	s_waitcnt vmcnt(63)
	v_cvt_pk_bf16_f32 v20, v12, v13
	v_cvt_pk_bf16_f32 v21, v14, v15
	global_store_dwordx2 v10, v[20:21], s[10:11]
	s_add_u32 s10, s10, 0x20000
	s_addc_u32 s11, s11, 0
	v_lshlrev_b32_e32 v16, 16, v90
	v_and_b32_e32 v17, 0xffff0000, v90
	v_pk_fma_f32 v[12:13], v[6:7], v[12:13], v[16:17]
	v_lshlrev_b32_e32 v16, 16, v91
	v_and_b32_e32 v17, 0xffff0000, v91
	v_pk_fma_f32 v[14:15], v[6:7], v[14:15], v[16:17]
	s_waitcnt vmcnt(63)
	v_cvt_pk_bf16_f32 v20, v12, v13
	v_cvt_pk_bf16_f32 v21, v14, v15
	global_store_dwordx2 v10, v[20:21], s[10:11]
	s_add_u32 s10, s10, 0x20000
	s_addc_u32 s11, s11, 0
	v_lshlrev_b32_e32 v16, 16, v92
	v_and_b32_e32 v17, 0xffff0000, v92
	v_pk_fma_f32 v[12:13], v[6:7], v[12:13], v[16:17]
	v_lshlrev_b32_e32 v16, 16, v93
	v_and_b32_e32 v17, 0xffff0000, v93
	v_pk_fma_f32 v[14:15], v[6:7], v[14:15], v[16:17]
	s_waitcnt vmcnt(63)
	v_cvt_pk_bf16_f32 v20, v12, v13
	v_cvt_pk_bf16_f32 v21, v14, v15
	global_store_dwordx2 v10, v[20:21], s[10:11]
	s_add_u32 s10, s10, 0x20000
	s_addc_u32 s11, s11, 0
	v_lshlrev_b32_e32 v16, 16, v94
	v_and_b32_e32 v17, 0xffff0000, v94
	v_pk_fma_f32 v[12:13], v[6:7], v[12:13], v[16:17]
	v_lshlrev_b32_e32 v16, 16, v95
	v_and_b32_e32 v17, 0xffff0000, v95
	v_pk_fma_f32 v[14:15], v[6:7], v[14:15], v[16:17]
	s_waitcnt vmcnt(63)
	v_cvt_pk_bf16_f32 v20, v12, v13
	v_cvt_pk_bf16_f32 v21, v14, v15
	global_store_dwordx2 v10, v[20:21], s[10:11]
	s_add_u32 s10, s10, 0x20000
	s_addc_u32 s11, s11, 0
	v_lshlrev_b32_e32 v16, 16, v96
	v_and_b32_e32 v17, 0xffff0000, v96
	v_pk_fma_f32 v[12:13], v[6:7], v[12:13], v[16:17]
	v_lshlrev_b32_e32 v16, 16, v97
	v_and_b32_e32 v17, 0xffff0000, v97
	v_pk_fma_f32 v[14:15], v[6:7], v[14:15], v[16:17]
	s_waitcnt vmcnt(63)
	v_cvt_pk_bf16_f32 v20, v12, v13
	v_cvt_pk_bf16_f32 v21, v14, v15
	global_store_dwordx2 v10, v[20:21], s[10:11]
	s_add_u32 s10, s10, 0x20000
	s_addc_u32 s11, s11, 0
	v_lshlrev_b32_e32 v16, 16, v98
	v_and_b32_e32 v17, 0xffff0000, v98
	v_pk_fma_f32 v[12:13], v[6:7], v[12:13], v[16:17]
	v_lshlrev_b32_e32 v16, 16, v99
	v_and_b32_e32 v17, 0xffff0000, v99
	v_pk_fma_f32 v[14:15], v[6:7], v[14:15], v[16:17]
	s_waitcnt vmcnt(63)
; DI unsigned pk2(float lo, float hi) { unsigned r; asm volatile("v_cvt_pk_bf16_f32 %0, %1, %2" : "=v"(r) : "v"(lo), "v"(hi)); return r; }
; DI float bflo(unsigned u) { return __uint_as_float(u << 16); }
; DI float bfhi(unsigned u) { return __uint_as_float(u & 0xffff0000u); }
; DI void scan_unit(const Params& p, int hf, int su, int tid) {
;     ...
;       for (int c = 0; c < 64; ++c) {
;         uint2* q = (uint2*)(ptr + (size_t)c * 4 * 16384); const uint2 v = *q;
;         uint2 w; w.x = pk2(S0, S1); w.y = pk2(S2, S3); *q = w;
;         S0 = S0 * dc + bflo(v.x); S1 = S1 * dc + bfhi(v.x); S2 = S2 * dc + bflo(v.y); S3 = S3 * dc + bfhi(v.y);
;       }
	v_cvt_pk_bf16_f32 v20, v12, v13
	v_cvt_pk_bf16_f32 v21, v14, v15
	global_store_dwordx2 v10, v[20:21], s[10:11]
	s_add_u32 s10, s10, 0x20000
	s_addc_u32 s11, s11, 0
	v_lshlrev_b32_e32 v16, 16, v100
	v_and_b32_e32 v17, 0xffff0000, v100
	v_pk_fma_f32 v[12:13], v[6:7], v[12:13], v[16:17]
	v_lshlrev_b32_e32 v16, 16, v101
	v_and_b32_e32 v17, 0xffff0000, v101
	v_pk_fma_f32 v[14:15], v[6:7], v[14:15], v[16:17]
	s_waitcnt vmcnt(63)
	v_cvt_pk_bf16_f32 v20, v12, v13
	v_cvt_pk_bf16_f32 v21, v14, v15
	global_store_dwordx2 v10, v[20:21], s[10:11]
	s_add_u32 s10, s10, 0x20000
	s_addc_u32 s11, s11, 0
	v_lshlrev_b32_e32 v16, 16, v102
	v_and_b32_e32 v17, 0xffff0000, v102
	v_pk_fma_f32 v[12:13], v[6:7], v[12:13], v[16:17]
	v_lshlrev_b32_e32 v16, 16, v103
	v_and_b32_e32 v17, 0xffff0000, v103
	v_pk_fma_f32 v[14:15], v[6:7], v[14:15], v[16:17]
	s_waitcnt vmcnt(63)
	v_cvt_pk_bf16_f32 v20, v12, v13
	v_cvt_pk_bf16_f32 v21, v14, v15
	global_store_dwordx2 v10, v[20:21], s[10:11]
	s_add_u32 s10, s10, 0x20000
	s_addc_u32 s11, s11, 0
	v_lshlrev_b32_e32 v16, 16, v104
	v_and_b32_e32 v17, 0xffff0000, v104
	v_pk_fma_f32 v[12:13], v[6:7], v[12:13], v[16:17]
	v_lshlrev_b32_e32 v16, 16, v105
	v_and_b32_e32 v17, 0xffff0000, v105
	v_pk_fma_f32 v[14:15], v[6:7], v[14:15], v[16:17]
	s_waitcnt vmcnt(63)
	v_cvt_pk_bf16_f32 v20, v12, v13
	v_cvt_pk_bf16_f32 v21, v14, v15
	global_store_dwordx2 v10, v[20:21], s[10:11]
	s_add_u32 s10, s10, 0x20000
	s_addc_u32 s11, s11, 0
	v_lshlrev_b32_e32 v16, 16, v106
	v_and_b32_e32 v17, 0xffff0000, v106
	v_pk_fma_f32 v[12:13], v[6:7], v[12:13], v[16:17]
	v_lshlrev_b32_e32 v16, 16, v107
	v_and_b32_e32 v17, 0xffff0000, v107
	v_pk_fma_f32 v[14:15], v[6:7], v[14:15], v[16:17]
	s_waitcnt vmcnt(63)
	v_cvt_pk_bf16_f32 v20, v12, v13
	v_cvt_pk_bf16_f32 v21, v14, v15
	global_store_dwordx2 v10, v[20:21], s[10:11]
	s_add_u32 s10, s10, 0x20000
	s_addc_u32 s11, s11, 0
	v_lshlrev_b32_e32 v16, 16, v108
	v_and_b32_e32 v17, 0xffff0000, v108
	v_pk_fma_f32 v[12:13], v[6:7], v[12:13], v[16:17]
	v_lshlrev_b32_e32 v16, 16, v109
	v_and_b32_e32 v17, 0xffff0000, v109
	v_pk_fma_f32 v[14:15], v[6:7], v[14:15], v[16:17]
	s_waitcnt vmcnt(63)
	v_cvt_pk_bf16_f32 v20, v12, v13
	v_cvt_pk_bf16_f32 v21, v14, v15
	global_store_dwordx2 v10, v[20:21], s[10:11]
	s_add_u32 s10, s10, 0x20000
	s_addc_u32 s11, s11, 0
	v_lshlrev_b32_e32 v16, 16, v110
	v_and_b32_e32 v17, 0xffff0000, v110
	v_pk_fma_f32 v[12:13], v[6:7], v[12:13], v[16:17]
	v_lshlrev_b32_e32 v16, 16, v111
	v_and_b32_e32 v17, 0xffff0000, v111
	v_pk_fma_f32 v[14:15], v[6:7], v[14:15], v[16:17]
	s_waitcnt vmcnt(63)
	v_cvt_pk_bf16_f32 v20, v12, v13
	v_cvt_pk_bf16_f32 v21, v14, v15
	global_store_dwordx2 v10, v[20:21], s[10:11]
	s_add_u32 s10, s10, 0x20000
	s_addc_u32 s11, s11, 0
	v_lshlrev_b32_e32 v16, 16, v112
	v_and_b32_e32 v17, 0xffff0000, v112
	v_pk_fma_f32 v[12:13], v[6:7], v[12:13], v[16:17]
	v_lshlrev_b32_e32 v16, 16, v113
	v_and_b32_e32 v17, 0xffff0000, v113
	v_pk_fma_f32 v[14:15], v[6:7], v[14:15], v[16:17]
	s_waitcnt vmcnt(63)
	v_cvt_pk_bf16_f32 v20, v12, v13
	v_cvt_pk_bf16_f32 v21, v14, v15
	global_store_dwordx2 v10, v[20:21], s[10:11]
	s_add_u32 s10, s10, 0x20000
	s_addc_u32 s11, s11, 0
	v_lshlrev_b32_e32 v16, 16, v114
	v_and_b32_e32 v17, 0xffff0000, v114
	v_pk_fma_f32 v[12:13], v[6:7], v[12:13], v[16:17]
	v_lshlrev_b32_e32 v16, 16, v115
	v_and_b32_e32 v17, 0xffff0000, v115
	v_pk_fma_f32 v[14:15], v[6:7], v[14:15], v[16:17]
	s_waitcnt vmcnt(63)
	v_cvt_pk_bf16_f32 v20, v12, v13
	v_cvt_pk_bf16_f32 v21, v14, v15
	global_store_dwordx2 v10, v[20:21], s[10:11]
	s_add_u32 s10, s10, 0x20000
	s_addc_u32 s11, s11, 0
	v_lshlrev_b32_e32 v16, 16, v116
	v_and_b32_e32 v17, 0xffff0000, v116
	v_pk_fma_f32 v[12:13], v[6:7], v[12:13], v[16:17]
	v_lshlrev_b32_e32 v16, 16, v117
	v_and_b32_e32 v17, 0xffff0000, v117
	v_pk_fma_f32 v[14:15], v[6:7], v[14:15], v[16:17]
	s_waitcnt vmcnt(63)
	v_cvt_pk_bf16_f32 v20, v12, v13
	v_cvt_pk_bf16_f32 v21, v14, v15
	global_store_dwordx2 v10, v[20:21], s[10:11]
	s_add_u32 s10, s10, 0x20000
	s_addc_u32 s11, s11, 0
	v_lshlrev_b32_e32 v16, 16, v118
	v_and_b32_e32 v17, 0xffff0000, v118
	v_pk_fma_f32 v[12:13], v[6:7], v[12:13], v[16:17]
	v_lshlrev_b32_e32 v16, 16, v119
	v_and_b32_e32 v17, 0xffff0000, v119
	v_pk_fma_f32 v[14:15], v[6:7], v[14:15], v[16:17]
	s_waitcnt vmcnt(63)
	v_cvt_pk_bf16_f32 v20, v12, v13
	v_cvt_pk_bf16_f32 v21, v14, v15
	global_store_dwordx2 v10, v[20:21], s[10:11]
	s_add_u32 s10, s10, 0x20000
	s_addc_u32 s11, s11, 0
	v_lshlrev_b32_e32 v16, 16, v120
	v_and_b32_e32 v17, 0xffff0000, v120
	v_pk_fma_f32 v[12:13], v[6:7], v[12:13], v[16:17]
	v_lshlrev_b32_e32 v16, 16, v121
	v_and_b32_e32 v17, 0xffff0000, v121
	v_pk_fma_f32 v[14:15], v[6:7], v[14:15], v[16:17]
	s_waitcnt vmcnt(63)
	v_cvt_pk_bf16_f32 v20, v12, v13
	v_cvt_pk_bf16_f32 v21, v14, v15
	global_store_dwordx2 v10, v[20:21], s[10:11]
	s_add_u32 s10, s10, 0x20000
	s_addc_u32 s11, s11, 0
	v_lshlrev_b32_e32 v16, 16, v122
	v_and_b32_e32 v17, 0xffff0000, v122
	v_pk_fma_f32 v[12:13], v[6:7], v[12:13], v[16:17]
	v_lshlrev_b32_e32 v16, 16, v123
	v_and_b32_e32 v17, 0xffff0000, v123
	v_pk_fma_f32 v[14:15], v[6:7], v[14:15], v[16:17]
	s_waitcnt vmcnt(63)
	v_cvt_pk_bf16_f32 v20, v12, v13
	v_cvt_pk_bf16_f32 v21, v14, v15
	global_store_dwordx2 v10, v[20:21], s[10:11]
	s_add_u32 s10, s10, 0x20000
	s_addc_u32 s11, s11, 0
	v_lshlrev_b32_e32 v16, 16, v124
	v_and_b32_e32 v17, 0xffff0000, v124
	v_pk_fma_f32 v[12:13], v[6:7], v[12:13], v[16:17]
	v_lshlrev_b32_e32 v16, 16, v125
	v_and_b32_e32 v17, 0xffff0000, v125
	v_pk_fma_f32 v[14:15], v[6:7], v[14:15], v[16:17]
	s_waitcnt vmcnt(63)
; DI unsigned pk2(float lo, float hi) { unsigned r; asm volatile("v_cvt_pk_bf16_f32 %0, %1, %2" : "=v"(r) : "v"(lo), "v"(hi)); return r; }
; DI float bflo(unsigned u) { return __uint_as_float(u << 16); }
; DI float bfhi(unsigned u) { return __uint_as_float(u & 0xffff0000u); }
; DI void scan_unit(const Params& p, int hf, int su, int tid) {
;     ...
;       for (int c = 0; c < 64; ++c) {
;         uint2* q = (uint2*)(ptr + (size_t)c * 4 * 16384); const uint2 v = *q;
;         uint2 w; w.x = pk2(S0, S1); w.y = pk2(S2, S3); *q = w;
;         S0 = S0 * dc + bflo(v.x); S1 = S1 * dc + bfhi(v.x); S2 = S2 * dc + bflo(v.y); S3 = S3 * dc + bfhi(v.y);
;       }
	v_cvt_pk_bf16_f32 v20, v12, v13
	v_cvt_pk_bf16_f32 v21, v14, v15
	global_store_dwordx2 v10, v[20:21], s[10:11]
	s_add_u32 s10, s10, 0x20000
	s_addc_u32 s11, s11, 0
	v_lshlrev_b32_e32 v16, 16, v126
	v_and_b32_e32 v17, 0xffff0000, v126
	v_pk_fma_f32 v[12:13], v[6:7], v[12:13], v[16:17]
	v_lshlrev_b32_e32 v16, 16, v127
	v_and_b32_e32 v17, 0xffff0000, v127
	v_pk_fma_f32 v[14:15], v[6:7], v[14:15], v[16:17]
	s_waitcnt vmcnt(63)
	v_cvt_pk_bf16_f32 v20, v12, v13
	v_cvt_pk_bf16_f32 v21, v14, v15
	global_store_dwordx2 v10, v[20:21], s[10:11]
	s_add_u32 s10, s10, 0x20000
	s_addc_u32 s11, s11, 0
	v_lshlrev_b32_e32 v16, 16, v128
	v_and_b32_e32 v17, 0xffff0000, v128
	v_pk_fma_f32 v[12:13], v[6:7], v[12:13], v[16:17]
	v_lshlrev_b32_e32 v16, 16, v129
	v_and_b32_e32 v17, 0xffff0000, v129
	v_pk_fma_f32 v[14:15], v[6:7], v[14:15], v[16:17]
	s_waitcnt vmcnt(63)
	v_cvt_pk_bf16_f32 v20, v12, v13
	v_cvt_pk_bf16_f32 v21, v14, v15
	global_store_dwordx2 v10, v[20:21], s[10:11]
	s_add_u32 s10, s10, 0x20000
	s_addc_u32 s11, s11, 0
	v_lshlrev_b32_e32 v16, 16, v130
	v_and_b32_e32 v17, 0xffff0000, v130
	v_pk_fma_f32 v[12:13], v[6:7], v[12:13], v[16:17]
	v_lshlrev_b32_e32 v16, 16, v131
	v_and_b32_e32 v17, 0xffff0000, v131
	v_pk_fma_f32 v[14:15], v[6:7], v[14:15], v[16:17]
	s_waitcnt vmcnt(63)
	v_cvt_pk_bf16_f32 v20, v12, v13
	v_cvt_pk_bf16_f32 v21, v14, v15
	global_store_dwordx2 v10, v[20:21], s[10:11]
	s_add_u32 s10, s10, 0x20000
	s_addc_u32 s11, s11, 0
	v_lshlrev_b32_e32 v16, 16, v132
	v_and_b32_e32 v17, 0xffff0000, v132
	v_pk_fma_f32 v[12:13], v[6:7], v[12:13], v[16:17]
	v_lshlrev_b32_e32 v16, 16, v133
	v_and_b32_e32 v17, 0xffff0000, v133
	v_pk_fma_f32 v[14:15], v[6:7], v[14:15], v[16:17]
	s_waitcnt vmcnt(63)
	v_cvt_pk_bf16_f32 v20, v12, v13
	v_cvt_pk_bf16_f32 v21, v14, v15
	global_store_dwordx2 v10, v[20:21], s[10:11]
	s_add_u32 s10, s10, 0x20000
	s_addc_u32 s11, s11, 0
	v_lshlrev_b32_e32 v16, 16, v134
	v_and_b32_e32 v17, 0xffff0000, v134
	v_pk_fma_f32 v[12:13], v[6:7], v[12:13], v[16:17]
	v_lshlrev_b32_e32 v16, 16, v135
	v_and_b32_e32 v17, 0xffff0000, v135
	v_pk_fma_f32 v[14:15], v[6:7], v[14:15], v[16:17]
	s_waitcnt vmcnt(63)
	v_cvt_pk_bf16_f32 v20, v12, v13
	v_cvt_pk_bf16_f32 v21, v14, v15
	global_store_dwordx2 v10, v[20:21], s[10:11]
	s_add_u32 s10, s10, 0x20000
	s_addc_u32 s11, s11, 0
	v_lshlrev_b32_e32 v16, 16, v136
	v_and_b32_e32 v17, 0xffff0000, v136
	v_pk_fma_f32 v[12:13], v[6:7], v[12:13], v[16:17]
	v_lshlrev_b32_e32 v16, 16, v137
	v_and_b32_e32 v17, 0xffff0000, v137
	v_pk_fma_f32 v[14:15], v[6:7], v[14:15], v[16:17]
	s_waitcnt vmcnt(63)
	v_cvt_pk_bf16_f32 v20, v12, v13
	v_cvt_pk_bf16_f32 v21, v14, v15
	global_store_dwordx2 v10, v[20:21], s[10:11]
	s_add_u32 s10, s10, 0x20000
	s_addc_u32 s11, s11, 0
	v_lshlrev_b32_e32 v16, 16, v138
	v_and_b32_e32 v17, 0xffff0000, v138
	v_pk_fma_f32 v[12:13], v[6:7], v[12:13], v[16:17]
	v_lshlrev_b32_e32 v16, 16, v139
	v_and_b32_e32 v17, 0xffff0000, v139
	v_pk_fma_f32 v[14:15], v[6:7], v[14:15], v[16:17]
	s_waitcnt vmcnt(63)
	v_cvt_pk_bf16_f32 v20, v12, v13
	v_cvt_pk_bf16_f32 v21, v14, v15
	global_store_dwordx2 v10, v[20:21], s[10:11]
	s_add_u32 s10, s10, 0x20000
	s_addc_u32 s11, s11, 0
	v_lshlrev_b32_e32 v16, 16, v140
	v_and_b32_e32 v17, 0xffff0000, v140
	v_pk_fma_f32 v[12:13], v[6:7], v[12:13], v[16:17]
	v_lshlrev_b32_e32 v16, 16, v141
	v_and_b32_e32 v17, 0xffff0000, v141
	v_pk_fma_f32 v[14:15], v[6:7], v[14:15], v[16:17]
	s_waitcnt vmcnt(63)
	v_cvt_pk_bf16_f32 v20, v12, v13
	v_cvt_pk_bf16_f32 v21, v14, v15
	global_store_dwordx2 v10, v[20:21], s[10:11]
	s_add_u32 s10, s10, 0x20000
	s_addc_u32 s11, s11, 0
	v_lshlrev_b32_e32 v16, 16, v142
	v_and_b32_e32 v17, 0xffff0000, v142
	v_pk_fma_f32 v[12:13], v[6:7], v[12:13], v[16:17]
	v_lshlrev_b32_e32 v16, 16, v143
	v_and_b32_e32 v17, 0xffff0000, v143
	v_pk_fma_f32 v[14:15], v[6:7], v[14:15], v[16:17]
	s_waitcnt vmcnt(63)
	v_cvt_pk_bf16_f32 v20, v12, v13
	v_cvt_pk_bf16_f32 v21, v14, v15
	global_store_dwordx2 v10, v[20:21], s[10:11]
	s_add_u32 s10, s10, 0x20000
	s_addc_u32 s11, s11, 0
	v_lshlrev_b32_e32 v16, 16, v144
	v_and_b32_e32 v17, 0xffff0000, v144
	v_pk_fma_f32 v[12:13], v[6:7], v[12:13], v[16:17]
	v_lshlrev_b32_e32 v16, 16, v145
	v_and_b32_e32 v17, 0xffff0000, v145
	v_pk_fma_f32 v[14:15], v[6:7], v[14:15], v[16:17]
	s_waitcnt vmcnt(63)
	v_cvt_pk_bf16_f32 v20, v12, v13
	v_cvt_pk_bf16_f32 v21, v14, v15
	global_store_dwordx2 v10, v[20:21], s[10:11]
	s_add_u32 s10, s10, 0x20000
	s_addc_u32 s11, s11, 0
	v_lshlrev_b32_e32 v16, 16, v146
	v_and_b32_e32 v17, 0xffff0000, v146
	v_pk_fma_f32 v[12:13], v[6:7], v[12:13], v[16:17]
	v_lshlrev_b32_e32 v16, 16, v147
	v_and_b32_e32 v17, 0xffff0000, v147
	v_pk_fma_f32 v[14:15], v[6:7], v[14:15], v[16:17]
	s_waitcnt vmcnt(63)
	v_cvt_pk_bf16_f32 v20, v12, v13
	v_cvt_pk_bf16_f32 v21, v14, v15
	global_store_dwordx2 v10, v[20:21], s[10:11]
	s_add_u32 s10, s10, 0x20000
	s_addc_u32 s11, s11, 0
	v_lshlrev_b32_e32 v16, 16, v148
	v_and_b32_e32 v17, 0xffff0000, v148
	v_pk_fma_f32 v[12:13], v[6:7], v[12:13], v[16:17]
	v_lshlrev_b32_e32 v16, 16, v149
	v_and_b32_e32 v17, 0xffff0000, v149
	v_pk_fma_f32 v[14:15], v[6:7], v[14:15], v[16:17]
	s_waitcnt vmcnt(63)
; DI unsigned pk2(float lo, float hi) { unsigned r; asm volatile("v_cvt_pk_bf16_f32 %0, %1, %2" : "=v"(r) : "v"(lo), "v"(hi)); return r; }
; DI float bflo(unsigned u) { return __uint_as_float(u << 16); }
; DI float bfhi(unsigned u) { return __uint_as_float(u & 0xffff0000u); }
; DI void scan_unit(const Params& p, int hf, int su, int tid) {
;     ...
;       for (int c = 0; c < 64; ++c) {
;         uint2* q = (uint2*)(ptr + (size_t)c * 4 * 16384); const uint2 v = *q;
;         uint2 w; w.x = pk2(S0, S1); w.y = pk2(S2, S3); *q = w;
;         S0 = S0 * dc + bflo(v.x); S1 = S1 * dc + bfhi(v.x); S2 = S2 * dc + bflo(v.y); S3 = S3 * dc + bfhi(v.y);
;       }
	v_cvt_pk_bf16_f32 v20, v12, v13
	v_cvt_pk_bf16_f32 v21, v14, v15
	global_store_dwordx2 v10, v[20:21], s[10:11]
	s_add_u32 s10, s10, 0x20000
	s_addc_u32 s11, s11, 0
	v_lshlrev_b32_e32 v16, 16, v150
	v_and_b32_e32 v17, 0xffff0000, v150
	v_pk_fma_f32 v[12:13], v[6:7], v[12:13], v[16:17]
	v_lshlrev_b32_e32 v16, 16, v151
	v_and_b32_e32 v17, 0xffff0000, v151
	v_pk_fma_f32 v[14:15], v[6:7], v[14:15], v[16:17]
	s_waitcnt vmcnt(63)
	v_cvt_pk_bf16_f32 v20, v12, v13
	v_cvt_pk_bf16_f32 v21, v14, v15
	global_store_dwordx2 v10, v[20:21], s[10:11]
	s_add_u32 s10, s10, 0x20000
	s_addc_u32 s11, s11, 0
	v_lshlrev_b32_e32 v16, 16, v152
	v_and_b32_e32 v17, 0xffff0000, v152
	v_pk_fma_f32 v[12:13], v[6:7], v[12:13], v[16:17]
	v_lshlrev_b32_e32 v16, 16, v153
	v_and_b32_e32 v17, 0xffff0000, v153
	v_pk_fma_f32 v[14:15], v[6:7], v[14:15], v[16:17]
	s_waitcnt vmcnt(63)
	v_cvt_pk_bf16_f32 v20, v12, v13
	v_cvt_pk_bf16_f32 v21, v14, v15
	global_store_dwordx2 v10, v[20:21], s[10:11]
	s_add_u32 s10, s10, 0x20000
	s_addc_u32 s11, s11, 0
	v_lshlrev_b32_e32 v16, 16, v154
	v_and_b32_e32 v17, 0xffff0000, v154
	v_pk_fma_f32 v[12:13], v[6:7], v[12:13], v[16:17]
	v_lshlrev_b32_e32 v16, 16, v155
	v_and_b32_e32 v17, 0xffff0000, v155
	v_pk_fma_f32 v[14:15], v[6:7], v[14:15], v[16:17]
	s_waitcnt vmcnt(63)
	v_cvt_pk_bf16_f32 v20, v12, v13
	v_cvt_pk_bf16_f32 v21, v14, v15
	global_store_dwordx2 v10, v[20:21], s[10:11]
	s_add_u32 s10, s10, 0x20000
	s_addc_u32 s11, s11, 0
	v_lshlrev_b32_e32 v16, 16, v156
	v_and_b32_e32 v17, 0xffff0000, v156
	v_pk_fma_f32 v[12:13], v[6:7], v[12:13], v[16:17]
	v_lshlrev_b32_e32 v16, 16, v157
	v_and_b32_e32 v17, 0xffff0000, v157
	v_pk_fma_f32 v[14:15], v[6:7], v[14:15], v[16:17]
	s_waitcnt vmcnt(63)
	v_cvt_pk_bf16_f32 v20, v12, v13
	v_cvt_pk_bf16_f32 v21, v14, v15
	global_store_dwordx2 v10, v[20:21], s[10:11]
	s_add_u32 s10, s10, 0x20000
	s_addc_u32 s11, s11, 0
	v_lshlrev_b32_e32 v16, 16, v158
	v_and_b32_e32 v17, 0xffff0000, v158
	v_pk_fma_f32 v[12:13], v[6:7], v[12:13], v[16:17]
	v_lshlrev_b32_e32 v16, 16, v159
	v_and_b32_e32 v17, 0xffff0000, v159
	v_pk_fma_f32 v[14:15], v[6:7], v[14:15], v[16:17]
	s_waitcnt vmcnt(63)
	v_cvt_pk_bf16_f32 v20, v12, v13
	v_cvt_pk_bf16_f32 v21, v14, v15
	global_store_dwordx2 v10, v[20:21], s[10:11]
	s_add_u32 s10, s10, 0x20000
	s_addc_u32 s11, s11, 0
	v_lshlrev_b32_e32 v16, 16, v204
	v_and_b32_e32 v17, 0xffff0000, v204
	v_pk_fma_f32 v[12:13], v[6:7], v[12:13], v[16:17]
	v_lshlrev_b32_e32 v16, 16, v205
	v_and_b32_e32 v17, 0xffff0000, v205
	v_pk_fma_f32 v[14:15], v[6:7], v[14:15], v[16:17]
	s_waitcnt vmcnt(63)
	v_cvt_pk_bf16_f32 v20, v12, v13
	v_cvt_pk_bf16_f32 v21, v14, v15
	global_store_dwordx2 v10, v[20:21], s[10:11]
	s_add_u32 s10, s10, 0x20000
	s_addc_u32 s11, s11, 0
	v_lshlrev_b32_e32 v16, 16, v206
	v_and_b32_e32 v17, 0xffff0000, v206
	v_pk_fma_f32 v[12:13], v[6:7], v[12:13], v[16:17]
	v_lshlrev_b32_e32 v16, 16, v207
	v_and_b32_e32 v17, 0xffff0000, v207
	v_pk_fma_f32 v[14:15], v[6:7], v[14:15], v[16:17]
	s_waitcnt vmcnt(63)
	v_cvt_pk_bf16_f32 v20, v12, v13
	v_cvt_pk_bf16_f32 v21, v14, v15
	global_store_dwordx2 v10, v[20:21], s[10:11]
	s_add_u32 s10, s10, 0x20000
	s_addc_u32 s11, s11, 0
	v_lshlrev_b32_e32 v16, 16, v208
	v_and_b32_e32 v17, 0xffff0000, v208
	v_pk_fma_f32 v[12:13], v[6:7], v[12:13], v[16:17]
	v_lshlrev_b32_e32 v16, 16, v209
	v_and_b32_e32 v17, 0xffff0000, v209
	v_pk_fma_f32 v[14:15], v[6:7], v[14:15], v[16:17]
	s_waitcnt vmcnt(63)
	v_cvt_pk_bf16_f32 v20, v12, v13
	v_cvt_pk_bf16_f32 v21, v14, v15
	global_store_dwordx2 v10, v[20:21], s[10:11]
	s_add_u32 s10, s10, 0x20000
	s_addc_u32 s11, s11, 0
	v_lshlrev_b32_e32 v16, 16, v210
	v_and_b32_e32 v17, 0xffff0000, v210
	v_pk_fma_f32 v[12:13], v[6:7], v[12:13], v[16:17]
	v_lshlrev_b32_e32 v16, 16, v211
	v_and_b32_e32 v17, 0xffff0000, v211
	v_pk_fma_f32 v[14:15], v[6:7], v[14:15], v[16:17]
	s_waitcnt vmcnt(63)
	v_cvt_pk_bf16_f32 v20, v12, v13
	v_cvt_pk_bf16_f32 v21, v14, v15
	global_store_dwordx2 v10, v[20:21], s[10:11]
	s_add_u32 s10, s10, 0x20000
	s_addc_u32 s11, s11, 0
	v_lshlrev_b32_e32 v16, 16, v212
	v_and_b32_e32 v17, 0xffff0000, v212
	v_pk_fma_f32 v[12:13], v[6:7], v[12:13], v[16:17]
	v_lshlrev_b32_e32 v16, 16, v213
	v_and_b32_e32 v17, 0xffff0000, v213
	v_pk_fma_f32 v[14:15], v[6:7], v[14:15], v[16:17]
	s_waitcnt vmcnt(63)
	v_cvt_pk_bf16_f32 v20, v12, v13
	v_cvt_pk_bf16_f32 v21, v14, v15
	global_store_dwordx2 v10, v[20:21], s[10:11]
	s_add_u32 s10, s10, 0x20000
	s_addc_u32 s11, s11, 0
	v_lshlrev_b32_e32 v16, 16, v214
	v_and_b32_e32 v17, 0xffff0000, v214
	v_pk_fma_f32 v[12:13], v[6:7], v[12:13], v[16:17]
	v_lshlrev_b32_e32 v16, 16, v215
	v_and_b32_e32 v17, 0xffff0000, v215
	v_pk_fma_f32 v[14:15], v[6:7], v[14:15], v[16:17]
	s_waitcnt vmcnt(63)
	v_cvt_pk_bf16_f32 v20, v12, v13
	v_cvt_pk_bf16_f32 v21, v14, v15
	global_store_dwordx2 v10, v[20:21], s[10:11]
	s_add_u32 s10, s10, 0x20000
	s_addc_u32 s11, s11, 0
	v_lshlrev_b32_e32 v16, 16, v216
	v_and_b32_e32 v17, 0xffff0000, v216
	v_pk_fma_f32 v[12:13], v[6:7], v[12:13], v[16:17]
	v_lshlrev_b32_e32 v16, 16, v217
	v_and_b32_e32 v17, 0xffff0000, v217
	v_pk_fma_f32 v[14:15], v[6:7], v[14:15], v[16:17]
	s_waitcnt vmcnt(63)
	v_cvt_pk_bf16_f32 v20, v12, v13
	v_cvt_pk_bf16_f32 v21, v14, v15
	global_store_dwordx2 v10, v[20:21], s[10:11]
	s_add_u32 s10, s10, 0x20000
	s_addc_u32 s11, s11, 0
	v_lshlrev_b32_e32 v16, 16, v218
	v_and_b32_e32 v17, 0xffff0000, v218
	v_pk_fma_f32 v[12:13], v[6:7], v[12:13], v[16:17]
	v_lshlrev_b32_e32 v16, 16, v219
	v_and_b32_e32 v17, 0xffff0000, v219
	v_pk_fma_f32 v[14:15], v[6:7], v[14:15], v[16:17]
	s_branch .LBB0_576

; DI void fox_unit(const Params& p, int hf, int bl, int fh, int qb, unsigned char* shm, int tid, bool dry = false) {
;     ...
;     if (kt + 1 < nkt) {
;       const size_t r = (size_t)((kt + 1) * 64 + skey) * NP;
;       kreg = *(const uint4*)(projb + r + C_FK + fh * 64 + sdg * 8); vreg = *(const uint4*)(projb + r + C_FV + fh * 64 + sdg * 8);
;       if (tid < 64) freg = (Fref - F[(kt + 1) * 64 + tid]) * LOG2E;
;     }
.LBB0_606:
	v_add_u32_e32 v18, s17, v217
	v_mov_b64_e32 v[16:17], s[6:7]
	v_mad_i64_i32 v[16:17], s[4:5], v18, s65, v[16:17]
	v_lshl_add_u64 v[16:17], v[16:17], 0, s[2:3]
	v_lshl_add_u64 v[16:17], v[16:17], 0, v[160:161]
	v_add_co_u32_e32 v18, vcc, 0x1000, v16
	s_nop 1
	v_addc_co_u32_e32 v19, vcc, 0, v17, vcc
	v_add_co_u32_e32 v20, vcc, 0x2000, v16
	s_nop 1
	v_addc_co_u32_e32 v21, vcc, 0, v17, vcc
	s_mov_b32 s100, 0x270000
	s_mov_b32 s101, 0
	v_lshl_add_u64 v[100:101], v[18:19], 0, s[100:101]
	v_lshl_add_u64 v[102:103], v[20:21], 0, s[100:101]
	global_load_dwordx4 v[16:19], v[18:19], off offset:3072
	s_nop 0
	global_load_dwordx4 v[20:23], v[20:21], off
	s_and_saveexec_b64 s[4:5], s[0:1]
	s_cbranch_execz .LBB0_608
	v_add_u32_e32 v24, s17, v216
	v_ashrrev_i32_e32 v25, 31, v24
	v_lshl_add_u64 v[24:25], v[24:25], 2, s[8:9]
	global_load_dword v208, v[24:25], off
.LBB0_608:
	s_or_b64 exec, exec, s[4:5]
	global_load_dword v198, v[100:101], off offset:3072
	global_load_dword v199, v[102:103], off
	s_and_b32 s20, s21, 1
	v_cmp_le_i32_e32 vcc, s17, v212
	s_and_saveexec_b64 s[14:15], vcc
	s_cbranch_execz .LBB0_605

; DI void fox_unit(const Params& p, int hf, int bl, int fh, int qb, unsigned char* shm, int tid, bool dry = false) {
;     ...
;     if (kt + 1 < nkt) {
;       bf16_t* nK = (bf16_t*)(shm + (st ^ 1) * STG); bf16_t* nV = nK + 64 * 72; float* nF = (float*)(nV + 64 * 72);
;       *(uint4*)((unsigned char*)nK + kst) = kreg; *(uint4*)(nV + skey * 72 + sdg * 8) = vreg;
;       if (tid < 64) nF[tid] = freg;
;     }
.LBB0_614:
	s_xor_b32 s4, s20, 1
	s_mulk_i32 s4, 0x4900
	s_add_i32 s12, s4, 32
	s_waitcnt lgkmcnt(0)
	v_add_u32_e32 v24, s12, v210
	s_waitcnt vmcnt(3)
	ds_write_b128 v24, v[16:19]
	v_add3_u32 v24, s12, v211, v160
	s_waitcnt vmcnt(2)
	ds_write_b128 v24, v[20:23] offset:9216
	s_and_saveexec_b64 s[4:5], s[0:1]
	v_sub_f32_e32 v208, v192, v208
	v_lshl_add_u32 v24, v205, 2, s12
	v_mul_f32_e32 v208, 0x3fb8aa3b, v208
	ds_write_b32 v24, v208 offset:18432
	s_or_b64 exec, exec, s[4:5]

; DI unsigned pk2(float lo, float hi) { unsigned r; asm volatile("v_cvt_pk_bf16_f32 %0, %1, %2" : "=v"(r) : "v"(lo), "v"(hi)); return r; }
; DI float bflo(unsigned u) { return __uint_as_float(u << 16); }
; DI float bfhi(unsigned u) { return __uint_as_float(u & 0xffff0000u); }
; DI float silu_f(float x) { return x * __builtin_amdgcn_rcpf(1.0f + __expf(-x)); }
; DI float shx(float v, int m, int lane) { return __int_as_float(__builtin_amdgcn_ds_bpermute((lane ^ m) << 2, __float_as_int(v))); }
; DI void fox_unit(const Params& p, int hf, int bl, int fh, int qb, unsigned char* shm, int tid, bool dry = false) {
;     ...
;   for (int mi = 0; mi < 2; ++mi) {
;     float l = lsum[mi]; l += shx(l, 16, lane); l += shx(l, 32, lane);
;     const float inv = 1.0f / l;
;     bf16_t* gp = projb + (size_t)(qg0 + 16 * mi) * NP + C_FG + fh * 64 + 4 * fq;
; #pragma unroll
;     for (int d = 0; d < 4; ++d) {
;       const uint2 gv = *(const uint2*)(gp + 16 * d);
;       uint2 w;
;       w.x = pk2(o[mi][d][0] * inv * silu_f(bflo(gv.x)), o[mi][d][1] * inv * silu_f(bfhi(gv.x)));
;       w.y = pk2(o[mi][d][2] * inv * silu_f(bflo(gv.y)), o[mi][d][3] * inv * silu_f(bfhi(gv.y)));
;       if (!dry || inv == 1.2345e-30f) *(uint2*)(gp + 16 * d) = w;
;     }
.LBB0_620:
	ds_bpermute_b32 v0, v204, v128
	v_mov_b32_e32 v27, v161
	s_mov_b64 s[6:7], 0x3000
	s_movk_i32 s4, 0x3000
	s_waitcnt lgkmcnt(0)
	v_add_f32_e32 v0, v128, v0
	ds_bpermute_b32 v1, v169, v0
	s_waitcnt lgkmcnt(0)
	v_add_f32_e32 v0, v0, v1
	v_div_scale_f32 v1, s[0:1], v0, v0, 1.0
	v_rcp_f32_e32 v2, v1
	s_nop 0
	v_fma_f32 v3, -v1, v2, 1.0
	v_fmac_f32_e32 v2, v3, v2
	v_div_scale_f32 v3, vcc, 1.0, v0, 1.0
	v_mul_f32_e32 v4, v3, v2
	v_fma_f32 v5, -v1, v4, v3
	v_fmac_f32_e32 v4, v5, v2
	v_fma_f32 v1, -v1, v4, v3
	v_div_fmas_f32 v1, v1, v2, v4
	v_div_fixup_f32 v6, v1, v0, 1.0
	v_lshl_add_u64 v[2:3], v[126:127], 0, s[2:3]
	v_lshlrev_b64 v[0:1], 1, v[26:27]
	v_lshl_add_u64 v[4:5], v[2:3], 0, v[0:1]
	v_lshl_add_u64 v[2:3], v[4:5], 0, s[6:7]
	v_add_co_u32_e32 v4, vcc, s4, v4
	v_mul_f32_e32 v7, v144, v6
	s_nop 0
	v_addc_co_u32_e32 v5, vcc, 0, v5, vcc
	global_load_dwordx2 v[8:9], v[4:5], off
	s_waitcnt vmcnt(0)
	v_lshlrev_b32_e32 v10, 16, v8
	v_mul_f32_e32 v11, 0xbfb8aa3b, v10
	v_exp_f32_e32 v11, v11
	v_and_b32_e32 v8, 0xffff0000, v8
	v_add_f32_e32 v11, 1.0, v11
	v_rcp_f32_e32 v11, v11
	s_nop 0
	v_mul_f32_e32 v10, v11, v10
	v_mul_f32_e32 v11, 0xbfb8aa3b, v8
	v_exp_f32_e32 v11, v11
	v_mul_f32_e32 v7, v7, v10
	v_mul_f32_e32 v10, v145, v6
	v_add_f32_e32 v11, 1.0, v11
	v_rcp_f32_e32 v11, v11
	s_nop 0
	v_mul_f32_e32 v8, v11, v8
	v_mul_f32_e32 v8, v10, v8
	v_lshlrev_b32_e32 v10, 16, v9
	v_mul_f32_e32 v11, 0xbfb8aa3b, v10
	v_exp_f32_e32 v11, v11
	v_and_b32_e32 v9, 0xffff0000, v9
	v_cvt_pk_bf16_f32 v8, v7, v8
	v_mul_f32_e32 v7, v142, v6
	v_add_f32_e32 v11, 1.0, v11
	v_rcp_f32_e32 v11, v11
	s_nop 0
	v_mul_f32_e32 v10, v11, v10
	v_mul_f32_e32 v11, 0xbfb8aa3b, v9
	v_exp_f32_e32 v11, v11
	v_mul_f32_e32 v7, v7, v10
	v_mul_f32_e32 v10, v143, v6
	v_add_f32_e32 v11, 1.0, v11
	v_rcp_f32_e32 v11, v11
	s_nop 0
	v_mul_f32_e32 v9, v11, v9
	v_mul_f32_e32 v9, v10, v9
	v_cvt_pk_bf16_f32 v9, v7, v9
	global_store_dwordx2 v[4:5], v[8:9], off
	global_load_dwordx2 v[4:5], v[2:3], off offset:32
	v_mul_f32_e32 v7, v140, v6
	s_waitcnt vmcnt(0)
	v_lshlrev_b32_e32 v8, 16, v4
	v_mul_f32_e32 v9, 0xbfb8aa3b, v8
	v_exp_f32_e32 v9, v9
	v_and_b32_e32 v4, 0xffff0000, v4
	v_add_f32_e32 v9, 1.0, v9
	v_rcp_f32_e32 v9, v9
	s_nop 0
	v_mul_f32_e32 v8, v9, v8
	v_mul_f32_e32 v9, 0xbfb8aa3b, v4
	v_exp_f32_e32 v9, v9
	v_mul_f32_e32 v7, v7, v8
	v_mul_f32_e32 v8, v141, v6
	v_add_f32_e32 v9, 1.0, v9
	v_rcp_f32_e32 v9, v9
	s_nop 0
	v_mul_f32_e32 v4, v9, v4
	v_mul_f32_e32 v4, v8, v4
	v_lshlrev_b32_e32 v8, 16, v5
	v_mul_f32_e32 v9, 0xbfb8aa3b, v8
	v_exp_f32_e32 v9, v9
	v_and_b32_e32 v5, 0xffff0000, v5
	v_cvt_pk_bf16_f32 v4, v7, v4
	v_mul_f32_e32 v7, v138, v6
	v_add_f32_e32 v9, 1.0, v9
	v_rcp_f32_e32 v9, v9
	s_nop 0
	v_mul_f32_e32 v8, v9, v8
	v_mul_f32_e32 v9, 0xbfb8aa3b, v5
	v_exp_f32_e32 v9, v9
	v_mul_f32_e32 v7, v7, v8
	v_mul_f32_e32 v8, v139, v6
	v_add_f32_e32 v9, 1.0, v9
	v_rcp_f32_e32 v9, v9
	s_nop 0
	v_mul_f32_e32 v5, v9, v5
	v_mul_f32_e32 v5, v8, v5
	v_cvt_pk_bf16_f32 v5, v7, v5
	global_store_dwordx2 v[2:3], v[4:5], off offset:32
	global_load_dwordx2 v[4:5], v[2:3], off offset:64
	v_mul_f32_e32 v7, v136, v6
	s_waitcnt vmcnt(0)
	v_lshlrev_b32_e32 v8, 16, v4
	v_mul_f32_e32 v9, 0xbfb8aa3b, v8
	v_exp_f32_e32 v9, v9
	v_and_b32_e32 v4, 0xffff0000, v4
	v_add_f32_e32 v9, 1.0, v9
	v_rcp_f32_e32 v9, v9
	s_nop 0
	v_mul_f32_e32 v8, v9, v8
	v_mul_f32_e32 v9, 0xbfb8aa3b, v4
	v_exp_f32_e32 v9, v9
	v_mul_f32_e32 v7, v7, v8
	v_mul_f32_e32 v8, v137, v6
	v_add_f32_e32 v9, 1.0, v9
	v_rcp_f32_e32 v9, v9
	s_nop 0
	v_mul_f32_e32 v4, v9, v4
	v_mul_f32_e32 v4, v8, v4
	v_lshlrev_b32_e32 v8, 16, v5
	v_mul_f32_e32 v9, 0xbfb8aa3b, v8
	v_exp_f32_e32 v9, v9
	v_and_b32_e32 v5, 0xffff0000, v5
	v_cvt_pk_bf16_f32 v4, v7, v4
	v_mul_f32_e32 v7, v134, v6
	v_add_f32_e32 v9, 1.0, v9
	v_rcp_f32_e32 v9, v9
	s_nop 0
	v_mul_f32_e32 v8, v9, v8
	v_mul_f32_e32 v9, 0xbfb8aa3b, v5
	v_exp_f32_e32 v9, v9
	v_mul_f32_e32 v7, v7, v8
	v_mul_f32_e32 v8, v135, v6
	v_add_f32_e32 v9, 1.0, v9
	v_rcp_f32_e32 v9, v9
	s_nop 0
	v_mul_f32_e32 v5, v9, v5
	v_mul_f32_e32 v5, v8, v5
	v_cvt_pk_bf16_f32 v5, v7, v5
	global_store_dwordx2 v[2:3], v[4:5], off offset:64
	global_load_dwordx2 v[4:5], v[2:3], off offset:96
	v_mul_f32_e32 v7, v132, v6
	s_waitcnt vmcnt(0)
	v_lshlrev_b32_e32 v8, 16, v4
	v_mul_f32_e32 v9, 0xbfb8aa3b, v8
	v_exp_f32_e32 v9, v9
	v_and_b32_e32 v4, 0xffff0000, v4
	v_add_f32_e32 v9, 1.0, v9
	v_rcp_f32_e32 v9, v9
	s_nop 0
	v_mul_f32_e32 v8, v9, v8
	v_mul_f32_e32 v9, 0xbfb8aa3b, v4
	v_exp_f32_e32 v9, v9
	v_mul_f32_e32 v7, v7, v8
	v_mul_f32_e32 v8, v133, v6
	v_add_f32_e32 v9, 1.0, v9
	v_rcp_f32_e32 v9, v9
	s_nop 0
	v_mul_f32_e32 v4, v9, v4
	v_mul_f32_e32 v4, v8, v4
	v_lshlrev_b32_e32 v8, 16, v5
	v_mul_f32_e32 v9, 0xbfb8aa3b, v8
	v_exp_f32_e32 v9, v9
	v_cvt_pk_bf16_f32 v4, v7, v4
	v_mul_f32_e32 v7, v130, v6
	v_and_b32_e32 v5, 0xffff0000, v5
	v_add_f32_e32 v9, 1.0, v9
	v_rcp_f32_e32 v9, v9
	v_mul_f32_e32 v6, v131, v6
	v_mul_f32_e32 v8, v9, v8
	v_mul_f32_e32 v7, v7, v8
	v_mul_f32_e32 v8, 0xbfb8aa3b, v5
	v_exp_f32_e32 v8, v8
	s_nop 0
	v_add_f32_e32 v8, 1.0, v8
	v_rcp_f32_e32 v8, v8
	s_nop 0
	v_mul_f32_e32 v5, v8, v5
	v_mul_f32_e32 v5, v6, v5
	v_cvt_pk_bf16_f32 v5, v7, v5
	global_store_dwordx2 v[2:3], v[4:5], off offset:96
	ds_bpermute_b32 v2, v204, v129
	s_waitcnt lgkmcnt(0)
; DI unsigned pk2(float lo, float hi) { unsigned r; asm volatile("v_cvt_pk_bf16_f32 %0, %1, %2" : "=v"(r) : "v"(lo), "v"(hi)); return r; }
; DI float bflo(unsigned u) { return __uint_as_float(u << 16); }
; DI float bfhi(unsigned u) { return __uint_as_float(u & 0xffff0000u); }
; DI float silu_f(float x) { return x * __builtin_amdgcn_rcpf(1.0f + __expf(-x)); }
; DI float shx(float v, int m, int lane) { return __int_as_float(__builtin_amdgcn_ds_bpermute((lane ^ m) << 2, __float_as_int(v))); }
; DI void fox_unit(const Params& p, int hf, int bl, int fh, int qb, unsigned char* shm, int tid, bool dry = false) {
;     ...
;   for (int mi = 0; mi < 2; ++mi) {
;     float l = lsum[mi]; l += shx(l, 16, lane); l += shx(l, 32, lane);
;     const float inv = 1.0f / l;
;     bf16_t* gp = projb + (size_t)(qg0 + 16 * mi) * NP + C_FG + fh * 64 + 4 * fq;
; #pragma unroll
;     for (int d = 0; d < 4; ++d) {
;       const uint2 gv = *(const uint2*)(gp + 16 * d);
;       uint2 w;
;       w.x = pk2(o[mi][d][0] * inv * silu_f(bflo(gv.x)), o[mi][d][1] * inv * silu_f(bfhi(gv.x)));
;       w.y = pk2(o[mi][d][2] * inv * silu_f(bflo(gv.y)), o[mi][d][3] * inv * silu_f(bfhi(gv.y)));
;       if (!dry || inv == 1.2345e-30f) *(uint2*)(gp + 16 * d) = w;
;     }
	v_add_f32_e32 v2, v129, v2
	ds_bpermute_b32 v3, v169, v2
	s_waitcnt lgkmcnt(0)
	v_add_f32_e32 v2, v2, v3
	v_div_scale_f32 v3, s[0:1], v2, v2, 1.0
	v_rcp_f32_e32 v4, v3
	s_nop 0
	v_fma_f32 v5, -v3, v4, 1.0
	v_fmac_f32_e32 v4, v5, v4
	v_div_scale_f32 v5, vcc, 1.0, v2, 1.0
	v_mul_f32_e32 v6, v5, v4
	v_fma_f32 v7, -v3, v6, v5
	v_fmac_f32_e32 v6, v7, v4
	v_fma_f32 v3, -v3, v6, v5
	v_div_fmas_f32 v3, v3, v4, v6
	v_div_fixup_f32 v4, v3, v2, 1.0
	v_lshl_add_u64 v[2:3], v[108:109], 0, s[2:3]
	v_lshl_add_u64 v[2:3], v[2:3], 0, v[0:1]
	v_lshl_add_u64 v[0:1], v[2:3], 0, s[6:7]
	v_add_co_u32_e32 v2, vcc, s4, v2
	v_mul_f32_e32 v5, v124, v4
	s_nop 0
	v_addc_co_u32_e32 v3, vcc, 0, v3, vcc
	global_load_dwordx2 v[6:7], v[2:3], off
	v_readlane_b32 s6, v254, 55
	v_readlane_b32 s7, v254, 56
	s_waitcnt vmcnt(0)
	v_lshlrev_b32_e32 v8, 16, v6
	v_mul_f32_e32 v9, 0xbfb8aa3b, v8
	v_exp_f32_e32 v9, v9
	v_and_b32_e32 v6, 0xffff0000, v6
	v_add_f32_e32 v9, 1.0, v9
	v_rcp_f32_e32 v9, v9
	s_nop 0
	v_mul_f32_e32 v8, v9, v8
	v_mul_f32_e32 v9, 0xbfb8aa3b, v6
	v_exp_f32_e32 v9, v9
	v_mul_f32_e32 v5, v5, v8
	v_mul_f32_e32 v8, v125, v4
	v_add_f32_e32 v9, 1.0, v9
	v_rcp_f32_e32 v9, v9
	s_nop 0
	v_mul_f32_e32 v6, v9, v6
	v_mul_f32_e32 v6, v8, v6
	v_lshlrev_b32_e32 v8, 16, v7
	v_mul_f32_e32 v9, 0xbfb8aa3b, v8
	v_exp_f32_e32 v9, v9
	v_and_b32_e32 v7, 0xffff0000, v7
	v_cvt_pk_bf16_f32 v6, v5, v6
	v_mul_f32_e32 v5, v122, v4
	v_add_f32_e32 v9, 1.0, v9
	v_rcp_f32_e32 v9, v9
	s_nop 0
	v_mul_f32_e32 v8, v9, v8
	v_mul_f32_e32 v9, 0xbfb8aa3b, v7
	v_exp_f32_e32 v9, v9
	v_mul_f32_e32 v5, v5, v8
	v_mul_f32_e32 v8, v123, v4
	v_add_f32_e32 v9, 1.0, v9
	v_rcp_f32_e32 v9, v9
	s_nop 0
	v_mul_f32_e32 v7, v9, v7
	v_mul_f32_e32 v7, v8, v7
	v_cvt_pk_bf16_f32 v7, v5, v7
	global_store_dwordx2 v[2:3], v[6:7], off
	global_load_dwordx2 v[2:3], v[0:1], off offset:32
	v_mul_f32_e32 v5, v120, v4
	s_waitcnt vmcnt(0)
	v_lshlrev_b32_e32 v6, 16, v2
	v_mul_f32_e32 v7, 0xbfb8aa3b, v6
	v_exp_f32_e32 v7, v7
	v_and_b32_e32 v2, 0xffff0000, v2
	v_add_f32_e32 v7, 1.0, v7
	v_rcp_f32_e32 v7, v7
	s_nop 0
	v_mul_f32_e32 v6, v7, v6
	v_mul_f32_e32 v7, 0xbfb8aa3b, v2
	v_exp_f32_e32 v7, v7
	v_mul_f32_e32 v5, v5, v6
	v_mul_f32_e32 v6, v121, v4
	v_add_f32_e32 v7, 1.0, v7
	v_rcp_f32_e32 v7, v7
	s_nop 0
	v_mul_f32_e32 v2, v7, v2
	v_mul_f32_e32 v2, v6, v2
	v_lshlrev_b32_e32 v6, 16, v3
	v_mul_f32_e32 v7, 0xbfb8aa3b, v6
	v_exp_f32_e32 v7, v7
	v_and_b32_e32 v3, 0xffff0000, v3
	v_cvt_pk_bf16_f32 v2, v5, v2
	v_mul_f32_e32 v5, v118, v4
	v_add_f32_e32 v7, 1.0, v7
	v_rcp_f32_e32 v7, v7
	s_nop 0
	v_mul_f32_e32 v6, v7, v6
	v_mul_f32_e32 v7, 0xbfb8aa3b, v3
	v_exp_f32_e32 v7, v7
	v_mul_f32_e32 v5, v5, v6
	v_mul_f32_e32 v6, v119, v4
	v_add_f32_e32 v7, 1.0, v7
	v_rcp_f32_e32 v7, v7
	s_nop 0
	v_mul_f32_e32 v3, v7, v3
	v_mul_f32_e32 v3, v6, v3
	v_cvt_pk_bf16_f32 v3, v5, v3
	global_store_dwordx2 v[0:1], v[2:3], off offset:32
	global_load_dwordx2 v[2:3], v[0:1], off offset:64
	v_mul_f32_e32 v5, v116, v4
	s_waitcnt vmcnt(0)
	v_lshlrev_b32_e32 v6, 16, v2
	v_mul_f32_e32 v7, 0xbfb8aa3b, v6
	v_exp_f32_e32 v7, v7
	v_and_b32_e32 v2, 0xffff0000, v2
	v_add_f32_e32 v7, 1.0, v7
	v_rcp_f32_e32 v7, v7
	s_nop 0
	v_mul_f32_e32 v6, v7, v6
	v_mul_f32_e32 v7, 0xbfb8aa3b, v2
	v_exp_f32_e32 v7, v7
	v_mul_f32_e32 v5, v5, v6
	v_mul_f32_e32 v6, v117, v4
	v_add_f32_e32 v7, 1.0, v7
	v_rcp_f32_e32 v7, v7
	s_nop 0
	v_mul_f32_e32 v2, v7, v2
	v_mul_f32_e32 v2, v6, v2
	v_lshlrev_b32_e32 v6, 16, v3
	v_mul_f32_e32 v7, 0xbfb8aa3b, v6
	v_exp_f32_e32 v7, v7
	v_and_b32_e32 v3, 0xffff0000, v3
	v_cvt_pk_bf16_f32 v2, v5, v2
	v_mul_f32_e32 v5, v114, v4
	v_add_f32_e32 v7, 1.0, v7
	v_rcp_f32_e32 v7, v7
	s_nop 0
	v_mul_f32_e32 v6, v7, v6
	v_mul_f32_e32 v7, 0xbfb8aa3b, v3
	v_exp_f32_e32 v7, v7
	v_mul_f32_e32 v5, v5, v6
	v_mul_f32_e32 v6, v115, v4
	v_add_f32_e32 v7, 1.0, v7
	v_rcp_f32_e32 v7, v7
	s_nop 0
	v_mul_f32_e32 v3, v7, v3
	v_mul_f32_e32 v3, v6, v3
	v_cvt_pk_bf16_f32 v3, v5, v3
	global_store_dwordx2 v[0:1], v[2:3], off offset:64
	global_load_dwordx2 v[2:3], v[0:1], off offset:96
	v_mul_f32_e32 v5, v112, v4
	s_waitcnt vmcnt(0)
	v_lshlrev_b32_e32 v6, 16, v2
	v_mul_f32_e32 v7, 0xbfb8aa3b, v6
	v_exp_f32_e32 v7, v7
	v_and_b32_e32 v2, 0xffff0000, v2
	v_add_f32_e32 v7, 1.0, v7
	v_rcp_f32_e32 v7, v7
	s_nop 0
	v_mul_f32_e32 v6, v7, v6
	v_mul_f32_e32 v7, 0xbfb8aa3b, v2
	v_exp_f32_e32 v7, v7
	v_mul_f32_e32 v5, v5, v6
	v_mul_f32_e32 v6, v113, v4
	v_add_f32_e32 v7, 1.0, v7
	v_rcp_f32_e32 v7, v7
	s_nop 0
	v_mul_f32_e32 v2, v7, v2
	v_mul_f32_e32 v2, v6, v2
	v_lshlrev_b32_e32 v6, 16, v3
	v_mul_f32_e32 v7, 0xbfb8aa3b, v6
	v_exp_f32_e32 v7, v7
	v_cvt_pk_bf16_f32 v2, v5, v2
	v_mul_f32_e32 v5, v110, v4
	v_and_b32_e32 v3, 0xffff0000, v3
	v_add_f32_e32 v7, 1.0, v7
	v_rcp_f32_e32 v7, v7
	v_mul_f32_e32 v4, v111, v4
	v_mul_f32_e32 v6, v7, v6
	v_mul_f32_e32 v5, v5, v6
	v_mul_f32_e32 v6, 0xbfb8aa3b, v3
	v_exp_f32_e32 v6, v6
	s_nop 0
	v_add_f32_e32 v6, 1.0, v6
	v_rcp_f32_e32 v6, v6
	s_nop 0
	v_mul_f32_e32 v3, v6, v3
	v_mul_f32_e32 v3, v4, v3
	v_cvt_pk_bf16_f32 v3, v5, v3
	global_store_dwordx2 v[0:1], v[2:3], off offset:96
	v_mov_b32_e32 v198, 0x7f800000
	v_mov_b32_e32 v199, 0x7fc00000

; DI unsigned pk2(float lo, float hi) { unsigned r; asm volatile("v_cvt_pk_bf16_f32 %0, %1, %2" : "=v"(r) : "v"(lo), "v"(hi)); return r; }
; DI float bflo(unsigned u) { return __uint_as_float(u << 16); }
; DI float bfhi(unsigned u) { return __uint_as_float(u & 0xffff0000u); }
; DI float silu_f(float x) { return x * __builtin_amdgcn_rcpf(1.0f + __expf(-x)); }
; DI float shx(float v, int m, int lane) { return __int_as_float(__builtin_amdgcn_ds_bpermute((lane ^ m) << 2, __float_as_int(v))); }
; DI void fox_unit(const Params& p, int hf, int bl, int fh, int qb, unsigned char* shm, int tid, bool dry = false) {
;     ...
;   for (int mi = 0; mi < 2; ++mi) {
;     float l = lsum[mi]; l += shx(l, 16, lane); l += shx(l, 32, lane);
;     const float inv = 1.0f / l;
;     bf16_t* gp = projb + (size_t)(qg0 + 16 * mi) * NP + C_FG + fh * 64 + 4 * fq;
; #pragma unroll
;     for (int d = 0; d < 4; ++d) {
;       const uint2 gv = *(const uint2*)(gp + 16 * d);
;       uint2 w;
;       w.x = pk2(o[mi][d][0] * inv * silu_f(bflo(gv.x)), o[mi][d][1] * inv * silu_f(bfhi(gv.x)));
;       w.y = pk2(o[mi][d][2] * inv * silu_f(bflo(gv.y)), o[mi][d][3] * inv * silu_f(bfhi(gv.y)));
;       if (!dry || inv == 1.2345e-30f) *(uint2*)(gp + 16 * d) = w;
;     }
.LBB0_635:
	ds_bpermute_b32 v0, v204, v128
	v_mov_b32_e32 v27, v161
	s_mov_b64 s[6:7], 0x3000
	s_movk_i32 s4, 0x3000
	s_waitcnt lgkmcnt(0)
	v_add_f32_e32 v0, v128, v0
	ds_bpermute_b32 v1, v169, v0
	s_waitcnt lgkmcnt(0)
	v_add_f32_e32 v0, v0, v1
	v_div_scale_f32 v1, s[0:1], v0, v0, 1.0
	v_rcp_f32_e32 v2, v1
	s_nop 0
	v_fma_f32 v3, -v1, v2, 1.0
	v_fmac_f32_e32 v2, v3, v2
	v_div_scale_f32 v3, vcc, 1.0, v0, 1.0
	v_mul_f32_e32 v4, v3, v2
	v_fma_f32 v5, -v1, v4, v3
	v_fmac_f32_e32 v4, v5, v2
	v_fma_f32 v1, -v1, v4, v3
	v_div_fmas_f32 v1, v1, v2, v4
	v_div_fixup_f32 v6, v1, v0, 1.0
	v_lshl_add_u64 v[2:3], v[126:127], 0, s[2:3]
	v_lshlrev_b64 v[0:1], 1, v[26:27]
	v_lshl_add_u64 v[4:5], v[2:3], 0, v[0:1]
	v_lshl_add_u64 v[2:3], v[4:5], 0, s[6:7]
	v_add_co_u32_e32 v4, vcc, s4, v4
	v_mul_f32_e32 v7, v144, v6
	s_nop 0
	v_addc_co_u32_e32 v5, vcc, 0, v5, vcc
	global_load_dwordx2 v[8:9], v[4:5], off
	s_waitcnt vmcnt(0)
	v_lshlrev_b32_e32 v10, 16, v8
	v_mul_f32_e32 v11, 0xbfb8aa3b, v10
	v_exp_f32_e32 v11, v11
	v_and_b32_e32 v8, 0xffff0000, v8
	v_add_f32_e32 v11, 1.0, v11
	v_rcp_f32_e32 v11, v11
	s_nop 0
	v_mul_f32_e32 v10, v11, v10
	v_mul_f32_e32 v11, 0xbfb8aa3b, v8
	v_exp_f32_e32 v11, v11
	v_mul_f32_e32 v7, v7, v10
	v_mul_f32_e32 v10, v145, v6
	v_add_f32_e32 v11, 1.0, v11
	v_rcp_f32_e32 v11, v11
	s_nop 0
	v_mul_f32_e32 v8, v11, v8
	v_mul_f32_e32 v8, v10, v8
	v_lshlrev_b32_e32 v10, 16, v9
	v_mul_f32_e32 v11, 0xbfb8aa3b, v10
	v_exp_f32_e32 v11, v11
	v_and_b32_e32 v9, 0xffff0000, v9
	v_cvt_pk_bf16_f32 v8, v7, v8
	v_mul_f32_e32 v7, v142, v6
	v_add_f32_e32 v11, 1.0, v11
	v_rcp_f32_e32 v11, v11
	s_nop 0
	v_mul_f32_e32 v10, v11, v10
	v_mul_f32_e32 v11, 0xbfb8aa3b, v9
	v_exp_f32_e32 v11, v11
	v_mul_f32_e32 v7, v7, v10
	v_mul_f32_e32 v10, v143, v6
	v_add_f32_e32 v11, 1.0, v11
	v_rcp_f32_e32 v11, v11
	s_nop 0
	v_mul_f32_e32 v9, v11, v9
	v_mul_f32_e32 v9, v10, v9
	v_cvt_pk_bf16_f32 v9, v7, v9
	global_store_dwordx2 v[4:5], v[8:9], off
	global_load_dwordx2 v[4:5], v[2:3], off offset:32
	v_mul_f32_e32 v7, v140, v6
	s_waitcnt vmcnt(0)
	v_lshlrev_b32_e32 v8, 16, v4
	v_mul_f32_e32 v9, 0xbfb8aa3b, v8
	v_exp_f32_e32 v9, v9
	v_and_b32_e32 v4, 0xffff0000, v4
	v_add_f32_e32 v9, 1.0, v9
	v_rcp_f32_e32 v9, v9
	s_nop 0
	v_mul_f32_e32 v8, v9, v8
	v_mul_f32_e32 v9, 0xbfb8aa3b, v4
	v_exp_f32_e32 v9, v9
	v_mul_f32_e32 v7, v7, v8
	v_mul_f32_e32 v8, v141, v6
	v_add_f32_e32 v9, 1.0, v9
	v_rcp_f32_e32 v9, v9
	s_nop 0
	v_mul_f32_e32 v4, v9, v4
	v_mul_f32_e32 v4, v8, v4
	v_lshlrev_b32_e32 v8, 16, v5
	v_mul_f32_e32 v9, 0xbfb8aa3b, v8
	v_exp_f32_e32 v9, v9
	v_and_b32_e32 v5, 0xffff0000, v5
	v_cvt_pk_bf16_f32 v4, v7, v4
	v_mul_f32_e32 v7, v138, v6
	v_add_f32_e32 v9, 1.0, v9
	v_rcp_f32_e32 v9, v9
	s_nop 0
	v_mul_f32_e32 v8, v9, v8
	v_mul_f32_e32 v9, 0xbfb8aa3b, v5
	v_exp_f32_e32 v9, v9
	v_mul_f32_e32 v7, v7, v8
	v_mul_f32_e32 v8, v139, v6
	v_add_f32_e32 v9, 1.0, v9
	v_rcp_f32_e32 v9, v9
	s_nop 0
	v_mul_f32_e32 v5, v9, v5
	v_mul_f32_e32 v5, v8, v5
	v_cvt_pk_bf16_f32 v5, v7, v5
	global_store_dwordx2 v[2:3], v[4:5], off offset:32
	global_load_dwordx2 v[4:5], v[2:3], off offset:64
	v_mul_f32_e32 v7, v136, v6
	s_waitcnt vmcnt(0)
	v_lshlrev_b32_e32 v8, 16, v4
	v_mul_f32_e32 v9, 0xbfb8aa3b, v8
	v_exp_f32_e32 v9, v9
	v_and_b32_e32 v4, 0xffff0000, v4
	v_add_f32_e32 v9, 1.0, v9
	v_rcp_f32_e32 v9, v9
	s_nop 0
	v_mul_f32_e32 v8, v9, v8
	v_mul_f32_e32 v9, 0xbfb8aa3b, v4
	v_exp_f32_e32 v9, v9
	v_mul_f32_e32 v7, v7, v8
	v_mul_f32_e32 v8, v137, v6
	v_add_f32_e32 v9, 1.0, v9
	v_rcp_f32_e32 v9, v9
	s_nop 0
	v_mul_f32_e32 v4, v9, v4
	v_mul_f32_e32 v4, v8, v4
	v_lshlrev_b32_e32 v8, 16, v5
	v_mul_f32_e32 v9, 0xbfb8aa3b, v8
	v_exp_f32_e32 v9, v9
	v_and_b32_e32 v5, 0xffff0000, v5
	v_cvt_pk_bf16_f32 v4, v7, v4
	v_mul_f32_e32 v7, v134, v6
	v_add_f32_e32 v9, 1.0, v9
	v_rcp_f32_e32 v9, v9
	s_nop 0
	v_mul_f32_e32 v8, v9, v8
	v_mul_f32_e32 v9, 0xbfb8aa3b, v5
	v_exp_f32_e32 v9, v9
	v_mul_f32_e32 v7, v7, v8
	v_mul_f32_e32 v8, v135, v6
	v_add_f32_e32 v9, 1.0, v9
	v_rcp_f32_e32 v9, v9
	s_nop 0
	v_mul_f32_e32 v5, v9, v5
	v_mul_f32_e32 v5, v8, v5
	v_cvt_pk_bf16_f32 v5, v7, v5
	global_store_dwordx2 v[2:3], v[4:5], off offset:64
	global_load_dwordx2 v[4:5], v[2:3], off offset:96
	v_mul_f32_e32 v7, v132, v6
	s_waitcnt vmcnt(0)
	v_lshlrev_b32_e32 v8, 16, v4
	v_mul_f32_e32 v9, 0xbfb8aa3b, v8
	v_exp_f32_e32 v9, v9
	v_and_b32_e32 v4, 0xffff0000, v4
	v_add_f32_e32 v9, 1.0, v9
	v_rcp_f32_e32 v9, v9
	s_nop 0
	v_mul_f32_e32 v8, v9, v8
	v_mul_f32_e32 v9, 0xbfb8aa3b, v4
	v_exp_f32_e32 v9, v9
	v_mul_f32_e32 v7, v7, v8
	v_mul_f32_e32 v8, v133, v6
	v_add_f32_e32 v9, 1.0, v9
	v_rcp_f32_e32 v9, v9
	s_nop 0
	v_mul_f32_e32 v4, v9, v4
	v_mul_f32_e32 v4, v8, v4
	v_lshlrev_b32_e32 v8, 16, v5
	v_mul_f32_e32 v9, 0xbfb8aa3b, v8
	v_exp_f32_e32 v9, v9
	v_cvt_pk_bf16_f32 v4, v7, v4
	v_mul_f32_e32 v7, v130, v6
	v_and_b32_e32 v5, 0xffff0000, v5
	v_add_f32_e32 v9, 1.0, v9
	v_rcp_f32_e32 v9, v9
	v_mul_f32_e32 v6, v131, v6
	v_mul_f32_e32 v8, v9, v8
	v_mul_f32_e32 v7, v7, v8
	v_mul_f32_e32 v8, 0xbfb8aa3b, v5
	v_exp_f32_e32 v8, v8
	s_nop 0
	v_add_f32_e32 v8, 1.0, v8
	v_rcp_f32_e32 v8, v8
	s_nop 0
	v_mul_f32_e32 v5, v8, v5
	v_mul_f32_e32 v5, v6, v5
	v_cvt_pk_bf16_f32 v5, v7, v5
	global_store_dwordx2 v[2:3], v[4:5], off offset:96
	ds_bpermute_b32 v2, v204, v129
	s_waitcnt lgkmcnt(0)
; DI unsigned pk2(float lo, float hi) { unsigned r; asm volatile("v_cvt_pk_bf16_f32 %0, %1, %2" : "=v"(r) : "v"(lo), "v"(hi)); return r; }
; DI float bflo(unsigned u) { return __uint_as_float(u << 16); }
; DI float bfhi(unsigned u) { return __uint_as_float(u & 0xffff0000u); }
; DI float silu_f(float x) { return x * __builtin_amdgcn_rcpf(1.0f + __expf(-x)); }
; DI float shx(float v, int m, int lane) { return __int_as_float(__builtin_amdgcn_ds_bpermute((lane ^ m) << 2, __float_as_int(v))); }
; DI void fox_unit(const Params& p, int hf, int bl, int fh, int qb, unsigned char* shm, int tid, bool dry = false) {
;     ...
;   for (int mi = 0; mi < 2; ++mi) {
;     float l = lsum[mi]; l += shx(l, 16, lane); l += shx(l, 32, lane);
;     const float inv = 1.0f / l;
;     bf16_t* gp = projb + (size_t)(qg0 + 16 * mi) * NP + C_FG + fh * 64 + 4 * fq;
; #pragma unroll
;     for (int d = 0; d < 4; ++d) {
;       const uint2 gv = *(const uint2*)(gp + 16 * d);
;       uint2 w;
;       w.x = pk2(o[mi][d][0] * inv * silu_f(bflo(gv.x)), o[mi][d][1] * inv * silu_f(bfhi(gv.x)));
;       w.y = pk2(o[mi][d][2] * inv * silu_f(bflo(gv.y)), o[mi][d][3] * inv * silu_f(bfhi(gv.y)));
;       if (!dry || inv == 1.2345e-30f) *(uint2*)(gp + 16 * d) = w;
;     }
	v_add_f32_e32 v2, v129, v2
	ds_bpermute_b32 v3, v169, v2
	s_waitcnt lgkmcnt(0)
	v_add_f32_e32 v2, v2, v3
	v_div_scale_f32 v3, s[0:1], v2, v2, 1.0
	v_rcp_f32_e32 v4, v3
	s_nop 0
	v_fma_f32 v5, -v3, v4, 1.0
	v_fmac_f32_e32 v4, v5, v4
	v_div_scale_f32 v5, vcc, 1.0, v2, 1.0
	v_mul_f32_e32 v6, v5, v4
	v_fma_f32 v7, -v3, v6, v5
	v_fmac_f32_e32 v6, v7, v4
	v_fma_f32 v3, -v3, v6, v5
	v_div_fmas_f32 v3, v3, v4, v6
	v_div_fixup_f32 v4, v3, v2, 1.0
	v_lshl_add_u64 v[2:3], v[108:109], 0, s[2:3]
	v_lshl_add_u64 v[2:3], v[2:3], 0, v[0:1]
	v_lshl_add_u64 v[0:1], v[2:3], 0, s[6:7]
	v_add_co_u32_e32 v2, vcc, s4, v2
	v_mul_f32_e32 v5, v124, v4
	s_nop 0
	v_addc_co_u32_e32 v3, vcc, 0, v3, vcc
	global_load_dwordx2 v[6:7], v[2:3], off
	s_waitcnt vmcnt(0)
	v_lshlrev_b32_e32 v8, 16, v6
	v_mul_f32_e32 v9, 0xbfb8aa3b, v8
	v_exp_f32_e32 v9, v9
	v_and_b32_e32 v6, 0xffff0000, v6
	v_add_f32_e32 v9, 1.0, v9
	v_rcp_f32_e32 v9, v9
	s_nop 0
	v_mul_f32_e32 v8, v9, v8
	v_mul_f32_e32 v9, 0xbfb8aa3b, v6
	v_exp_f32_e32 v9, v9
	v_mul_f32_e32 v5, v5, v8
	v_mul_f32_e32 v8, v125, v4
	v_add_f32_e32 v9, 1.0, v9
	v_rcp_f32_e32 v9, v9
	s_nop 0
	v_mul_f32_e32 v6, v9, v6
	v_mul_f32_e32 v6, v8, v6
	v_lshlrev_b32_e32 v8, 16, v7
	v_mul_f32_e32 v9, 0xbfb8aa3b, v8
	v_exp_f32_e32 v9, v9
	v_and_b32_e32 v7, 0xffff0000, v7
	v_cvt_pk_bf16_f32 v6, v5, v6
	v_mul_f32_e32 v5, v122, v4
	v_add_f32_e32 v9, 1.0, v9
	v_rcp_f32_e32 v9, v9
	s_nop 0
	v_mul_f32_e32 v8, v9, v8
	v_mul_f32_e32 v9, 0xbfb8aa3b, v7
	v_exp_f32_e32 v9, v9
	v_mul_f32_e32 v5, v5, v8
	v_mul_f32_e32 v8, v123, v4
	v_add_f32_e32 v9, 1.0, v9
	v_rcp_f32_e32 v9, v9
	s_nop 0
	v_mul_f32_e32 v7, v9, v7
	v_mul_f32_e32 v7, v8, v7
	v_cvt_pk_bf16_f32 v7, v5, v7
	global_store_dwordx2 v[2:3], v[6:7], off
	global_load_dwordx2 v[2:3], v[0:1], off offset:32
	v_mul_f32_e32 v5, v120, v4
	s_waitcnt vmcnt(0)
	v_lshlrev_b32_e32 v6, 16, v2
	v_mul_f32_e32 v7, 0xbfb8aa3b, v6
	v_exp_f32_e32 v7, v7
	v_and_b32_e32 v2, 0xffff0000, v2
	v_add_f32_e32 v7, 1.0, v7
	v_rcp_f32_e32 v7, v7
	s_nop 0
	v_mul_f32_e32 v6, v7, v6
	v_mul_f32_e32 v7, 0xbfb8aa3b, v2
	v_exp_f32_e32 v7, v7
	v_mul_f32_e32 v5, v5, v6
	v_mul_f32_e32 v6, v121, v4
	v_add_f32_e32 v7, 1.0, v7
	v_rcp_f32_e32 v7, v7
	s_nop 0
	v_mul_f32_e32 v2, v7, v2
	v_mul_f32_e32 v2, v6, v2
	v_lshlrev_b32_e32 v6, 16, v3
	v_mul_f32_e32 v7, 0xbfb8aa3b, v6
	v_exp_f32_e32 v7, v7
	v_and_b32_e32 v3, 0xffff0000, v3
	v_cvt_pk_bf16_f32 v2, v5, v2
	v_mul_f32_e32 v5, v118, v4
	v_add_f32_e32 v7, 1.0, v7
	v_rcp_f32_e32 v7, v7
	s_nop 0
	v_mul_f32_e32 v6, v7, v6
	v_mul_f32_e32 v7, 0xbfb8aa3b, v3
	v_exp_f32_e32 v7, v7
	v_mul_f32_e32 v5, v5, v6
	v_mul_f32_e32 v6, v119, v4
	v_add_f32_e32 v7, 1.0, v7
	v_rcp_f32_e32 v7, v7
	s_nop 0
	v_mul_f32_e32 v3, v7, v3
	v_mul_f32_e32 v3, v6, v3
	v_cvt_pk_bf16_f32 v3, v5, v3
	global_store_dwordx2 v[0:1], v[2:3], off offset:32
	global_load_dwordx2 v[2:3], v[0:1], off offset:64
	v_mul_f32_e32 v5, v116, v4
	s_waitcnt vmcnt(0)
	v_lshlrev_b32_e32 v6, 16, v2
	v_mul_f32_e32 v7, 0xbfb8aa3b, v6
	v_exp_f32_e32 v7, v7
	v_and_b32_e32 v2, 0xffff0000, v2
	v_add_f32_e32 v7, 1.0, v7
	v_rcp_f32_e32 v7, v7
	s_nop 0
	v_mul_f32_e32 v6, v7, v6
	v_mul_f32_e32 v7, 0xbfb8aa3b, v2
	v_exp_f32_e32 v7, v7
	v_mul_f32_e32 v5, v5, v6
	v_mul_f32_e32 v6, v117, v4
	v_add_f32_e32 v7, 1.0, v7
	v_rcp_f32_e32 v7, v7
	s_nop 0
	v_mul_f32_e32 v2, v7, v2
	v_mul_f32_e32 v2, v6, v2
	v_lshlrev_b32_e32 v6, 16, v3
	v_mul_f32_e32 v7, 0xbfb8aa3b, v6
	v_exp_f32_e32 v7, v7
	v_and_b32_e32 v3, 0xffff0000, v3
	v_cvt_pk_bf16_f32 v2, v5, v2
	v_mul_f32_e32 v5, v114, v4
	v_add_f32_e32 v7, 1.0, v7
	v_rcp_f32_e32 v7, v7
	s_nop 0
	v_mul_f32_e32 v6, v7, v6
	v_mul_f32_e32 v7, 0xbfb8aa3b, v3
	v_exp_f32_e32 v7, v7
	v_mul_f32_e32 v5, v5, v6
	v_mul_f32_e32 v6, v115, v4
	v_add_f32_e32 v7, 1.0, v7
	v_rcp_f32_e32 v7, v7
	s_nop 0
	v_mul_f32_e32 v3, v7, v3
	v_mul_f32_e32 v3, v6, v3
	v_cvt_pk_bf16_f32 v3, v5, v3
	global_store_dwordx2 v[0:1], v[2:3], off offset:64
	global_load_dwordx2 v[2:3], v[0:1], off offset:96
	v_mul_f32_e32 v5, v112, v4
	s_waitcnt vmcnt(0)
	v_lshlrev_b32_e32 v6, 16, v2
	v_mul_f32_e32 v7, 0xbfb8aa3b, v6
	v_exp_f32_e32 v7, v7
	v_and_b32_e32 v2, 0xffff0000, v2
	v_add_f32_e32 v7, 1.0, v7
	v_rcp_f32_e32 v7, v7
	s_nop 0
	v_mul_f32_e32 v6, v7, v6
	v_mul_f32_e32 v7, 0xbfb8aa3b, v2
	v_exp_f32_e32 v7, v7
	v_mul_f32_e32 v5, v5, v6
	v_mul_f32_e32 v6, v113, v4
	v_add_f32_e32 v7, 1.0, v7
	v_rcp_f32_e32 v7, v7
	s_nop 0
	v_mul_f32_e32 v2, v7, v2
	v_mul_f32_e32 v2, v6, v2
	v_lshlrev_b32_e32 v6, 16, v3
	v_mul_f32_e32 v7, 0xbfb8aa3b, v6
	v_exp_f32_e32 v7, v7
	v_cvt_pk_bf16_f32 v2, v5, v2
	v_mul_f32_e32 v5, v110, v4
	v_and_b32_e32 v3, 0xffff0000, v3
	v_add_f32_e32 v7, 1.0, v7
	v_rcp_f32_e32 v7, v7
	v_mul_f32_e32 v4, v111, v4
	v_mul_f32_e32 v6, v7, v6
	v_mul_f32_e32 v5, v5, v6
	v_mul_f32_e32 v6, 0xbfb8aa3b, v3
	v_exp_f32_e32 v6, v6
	s_nop 0
	v_add_f32_e32 v6, 1.0, v6
	v_rcp_f32_e32 v6, v6
	s_nop 0
	v_mul_f32_e32 v3, v6, v3
	v_mul_f32_e32 v3, v4, v3
	v_cvt_pk_bf16_f32 v3, v5, v3
	global_store_dwordx2 v[0:1], v[2:3], off offset:96
	s_cbranch_execz .LBB0_501
	v_mov_b32_e32 v198, 0x7f800000
	v_mov_b32_e32 v199, 0x7fc00000
	s_branch .LBB0_572
